# attention K/V/bias-table LDS reads issued ahead into dedicated registers and V fragments read as conflict-free ds_read_b64 pairs (on top of fsub, pre, chain edits)
# speedup vs baseline: 1.0314x; 1.0151x over previous
; #define LAS __attribute__((address_space(3)))
; #define MFMA16(a, b, c) __builtin_amdgcn_mfma_f32_16x16x32_bf16((a), (b), (c), 0, 0, 0)
; __device__ __forceinline__ void attn_item(int item, const float* const* in, int l, unsigned char* ws, bf16_t* ybuf, LAS unsigned char* lds, int tid, int lane, int wave) {
;     ...
;     const float sink = in[15][l * 8 + hq];
; #pragma unroll
;     for (int qg = 0; qg < 4; ++qg) {
;         const int i0 = qhalf * 64 + qg * 16, iq = i0 + fr, s_lo = 2 * qhalf + (qg >> 1);
;         const size_t gt = (size_t)b * SEQ + nb * 128 + iq;
;         const bf16x8 Bq0 = Bq[qg][0], Bq1 = Bq[qg][1];
;         f32x4 acc[10];
; #pragma unroll
;         for (int r = 0; r < 10; ++r) { const LAS bf16_t* kp = KL + (16 * (2 * s_lo + r) + fr) * 72 + 8 * q;
;             f32x4 a = (f32x4){0.f, 0.f, 0.f, 0.f}; a = MFMA16(*(const LAS bf16x8*)kp, Bq0, a); a = MFMA16(*(const LAS bf16x8*)(kp + 32), Bq1, a); acc[r] = a; }
;         const int a1 = iq + 1, sft = (4 - (a1 & 3)) & 3, a4 = (a1 + sft) >> 2;
;         const LAS float* ct = CT + (hl * 4 + sft) * 384 + 128 + 4 * (4 * (2 * s_lo) + q - a4);
;         float mx = sink;
; #pragma unroll
;         for (int r = 0; r < 10; ++r) { const f32x4 tb = *(const LAS f32x4*)(ct + 16 * r); const bool dead = (nb == 0) && (2 * s_lo + r < 8);
; #pragma unroll
;             for (int jj = 0; jj < 4; ++jj) { float sc = acc[r][jj] * 0.125f + tb[jj]; sc = dead ? NEG_INF : sc; acc[r][jj] = sc; mx = fmaxf(mx, sc); } }
.LBB0_839:
	s_or_b64 exec, exec, s[14:15]
	s_add_i32 s14, s6, s70
	s_ashr_i32 s15, s14, 31
	v_readlane_b32 s48, v248, 55
	s_lshl_b64 s[14:15], s[14:15], 2
	v_readlane_b32 s52, v248, 59
	v_readlane_b32 s53, v248, 60
	s_add_u32 s14, s52, s14
	s_addc_u32 s15, s53, s15
	s_lshl_b32 s8, s8, 2
	v_lshl_add_u32 v80, v78, 4, 0
	v_bitop3_b32 v30, s8, 3, v52 bitop3:0x34
	s_movk_i32 s8, 0x600
	v_mul_lo_u32 v30, v30, s8
	s_add_i32 s8, 0, 0x12000
	v_mad_u32_u24 v81, v75, s39, v80
	s_waitcnt lgkmcnt(0)
	s_barrier
	v_add_u32_e32 v77, s8, v30
	ds_read_b128 v[30:33], v81
	ds_read_b128 v[34:37], v81 offset:64
	s_waitcnt lgkmcnt(1)
	v_mfma_f32_16x16x32_bf16 v[30:33], v[30:33], v[38:41], 0
	v_or_b32_e32 v76, -4, v52
	global_load_dword v74, v1, s[14:15]
	v_lshl_or_b32 v82, s1, 4, v78
	s_waitcnt lgkmcnt(0)
	v_mfma_f32_16x16x32_bf16 v[66:69], v[34:37], v[26:29], v[30:33]
	ds_read_b128 v[108:111], v81 offset:2368
	ds_read_b128 v[112:115], v81 offset:2304
	ds_read_b128 v[116:119], v81 offset:4672
	ds_read_b128 v[120:123], v81 offset:4608
	ds_read_b128 v[124:127], v81 offset:6976
	ds_read_b128 v[128:131], v81 offset:6912
	s_lshl_b32 s6, s1, 1
	s_cmp_eq_u32 s7, 0
	ds_read_b128 v[132:135], v81 offset:9280
	s_waitcnt lgkmcnt(5)
	v_mfma_f32_16x16x32_bf16 v[30:33], v[112:115], v[38:41], 0
	s_cselect_b64 s[42:43], -1, 0
	s_or_b32 s7, s1, s7
	s_cmp_eq_u32 s7, 0
	v_mfma_f32_16x16x32_bf16 v[62:65], v[108:111], v[26:29], v[30:33]
	ds_read_b128 v[136:139], v81 offset:9216
	s_cselect_b64 s[44:45], -1, 0
	v_lshlrev_b32_e32 v0, 3, v78
	s_nop 0
	ds_read_b128 v[140:143], v81 offset:11584
	s_waitcnt lgkmcnt(5)
	v_mfma_f32_16x16x32_bf16 v[30:33], v[120:123], v[38:41], 0
	v_sub_u32_e32 v83, v80, v0
	s_lshl_b32 s1, s1, 7
	s_lshl_b64 s[10:11], s[10:11], 1
	v_mfma_f32_16x16x32_bf16 v[58:61], v[116:119], v[26:29], v[30:33]
	ds_read_b128 v[144:147], v81 offset:11520
	s_add_i32 s38, s38, s72
	v_readlane_b32 s49, v248, 56
	s_nop 0
	ds_read_b128 v[108:111], v81 offset:18496
	s_waitcnt lgkmcnt(5)
	v_mfma_f32_16x16x32_bf16 v[30:33], v[128:131], v[38:41], 0
	v_readlane_b32 s50, v248, 57
	v_readlane_b32 s51, v248, 58
	v_readlane_b32 s54, v248, 61
	v_mfma_f32_16x16x32_bf16 v[54:57], v[124:127], v[26:29], v[30:33]
	ds_read_b128 v[112:115], v81 offset:13888
	v_readlane_b32 s55, v248, 62
	v_readlane_b32 s56, v248, 63
	s_nop 0
	ds_read_b128 v[116:119], v81 offset:13824
	s_waitcnt lgkmcnt(5)
	v_mfma_f32_16x16x32_bf16 v[30:33], v[136:139], v[38:41], 0
	v_readlane_b32 s57, v250, 0
	v_readlane_b32 s58, v250, 1
	v_readlane_b32 s59, v250, 2
	v_mfma_f32_16x16x32_bf16 v[50:53], v[132:135], v[26:29], v[30:33]
	ds_read_b128 v[120:123], v81 offset:16192
	v_readlane_b32 s60, v250, 3
	v_readlane_b32 s61, v250, 4
	s_nop 0
	ds_read_b128 v[124:127], v81 offset:16128
	s_waitcnt lgkmcnt(5)
	v_mfma_f32_16x16x32_bf16 v[30:33], v[144:147], v[38:41], 0
	ds_read_b128 v[128:131], v81 offset:18432
	v_readlane_b32 s62, v250, 5
	v_readlane_b32 s63, v250, 6
	v_mfma_f32_16x16x32_bf16 v[46:49], v[140:143], v[26:29], v[30:33]
	ds_read_b128 v[132:135], v81 offset:20736
	s_nop 2
	ds_read_b128 v[136:139], v81 offset:20800
	s_waitcnt lgkmcnt(5)
	v_mfma_f32_16x16x32_bf16 v[30:33], v[116:119], v[38:41], 0
	v_mfma_f32_16x16x32_bf16 v[42:45], v[112:115], v[26:29], v[30:33]
	s_nop 0
	s_nop 5
	s_nop 0
	s_waitcnt lgkmcnt(3)
	v_mfma_f32_16x16x32_bf16 v[30:33], v[124:127], v[38:41], 0
	v_mfma_f32_16x16x32_bf16 v[34:37], v[120:123], v[26:29], v[30:33]
	s_nop 6
	s_nop 0
	s_waitcnt lgkmcnt(2)
	v_mfma_f32_16x16x32_bf16 v[30:33], v[128:131], v[38:41], 0
	v_mfma_f32_16x16x32_bf16 v[30:33], v[108:111], v[26:29], v[30:33]
	s_nop 0
	s_waitcnt lgkmcnt(1)
	v_mfma_f32_16x16x32_bf16 v[38:41], v[132:135], v[38:41], 0
	s_nop 0
	s_waitcnt lgkmcnt(0)
	v_mfma_f32_16x16x32_bf16 v[26:29], v[136:139], v[26:29], v[38:41]
	s_nop 4
	v_sub_u32_e32 v38, v75, v76
	v_lshrrev_b32_e32 v38, 2, v38
	v_sub_u32_e32 v38, v82, v38
	v_lshl_add_u32 v84, v38, 4, v77
	ds_read_b128 v[108:111], v84 offset:512
	ds_read_b128 v[112:115], v84 offset:576
	ds_read_b128 v[116:119], v84 offset:640
	ds_read_b128 v[120:123], v84 offset:704
	ds_read_b128 v[124:127], v84 offset:768
	ds_read_b128 v[128:131], v84 offset:832
	s_waitcnt lgkmcnt(5)
	v_fmamk_f32 v38, v66, 0x3e000000, v108
	v_cndmask_b32_e64 v66, v38, v236, s[42:43]
	v_fmamk_f32 v38, v67, 0x3e000000, v109
	v_cndmask_b32_e64 v41, v38, v236, s[42:43]
	v_fmamk_f32 v38, v68, 0x3e000000, v110
	v_mov_b32_e32 v89, v111
	v_fmac_f32_e32 v89, 0x3e000000, v69
	v_cndmask_b32_e64 v40, v38, v236, s[42:43]
	v_cndmask_b32_e64 v38, v89, v236, s[42:43]
	ds_read_b128 v[132:135], v84 offset:896
	s_waitcnt vmcnt(0)
	v_max3_f32 v39, v74, v66, v41
	v_max3_f32 v39, v39, v40, v38
	s_waitcnt lgkmcnt(5)
	v_fmamk_f32 v62, v62, 0x3e000000, v112
	v_cndmask_b32_e64 v67, v62, v236, s[42:43]
	v_fmamk_f32 v62, v63, 0x3e000000, v113
	v_cndmask_b32_e64 v63, v62, v236, s[42:43]
	v_max3_f32 v68, v39, v67, v63
	v_fmamk_f32 v39, v64, 0x3e000000, v114
	v_mov_b32_e32 v89, v115
	v_fmac_f32_e32 v89, 0x3e000000, v65
	v_cndmask_b32_e64 v62, v39, v236, s[42:43]
	v_cndmask_b32_e64 v39, v89, v236, s[42:43]
	ds_read_b128 v[136:139], v84 offset:960
	v_max3_f32 v68, v68, v62, v39
	s_waitcnt lgkmcnt(5)
	v_fmamk_f32 v58, v58, 0x3e000000, v116
	v_cndmask_b32_e64 v65, v58, v236, s[42:43]
	v_fmamk_f32 v58, v59, 0x3e000000, v117
	v_cndmask_b32_e64 v64, v58, v236, s[42:43]
	v_fmamk_f32 v58, v60, 0x3e000000, v118
	v_mov_b32_e32 v89, v119
	v_fmac_f32_e32 v89, 0x3e000000, v61
	v_cndmask_b32_e64 v59, v58, v236, s[42:43]
	v_cndmask_b32_e64 v58, v89, v236, s[42:43]
	ds_read_b128 v[140:143], v84 offset:1024
	v_max3_f32 v68, v68, v65, v64
	v_max3_f32 v60, v68, v59, v58
	s_waitcnt lgkmcnt(5)
; #define LAS __attribute__((address_space(3)))
; __device__ __forceinline__ void attn_item(int item, const float* const* in, int l, unsigned char* ws, bf16_t* ybuf, LAS unsigned char* lds, int tid, int lane, int wave) {
;     ...
;         float mx = sink;
; #pragma unroll
;         for (int r = 0; r < 10; ++r) { const f32x4 tb = *(const LAS f32x4*)(ct + 16 * r); const bool dead = (nb == 0) && (2 * s_lo + r < 8);
; #pragma unroll
;             for (int jj = 0; jj < 4; ++jj) { float sc = acc[r][jj] * 0.125f + tb[jj]; sc = dead ? NEG_INF : sc; acc[r][jj] = sc; mx = fmaxf(mx, sc); } }
;         mx = fmaxf(mx, __shfl_xor(mx, 16)); mx = fmaxf(mx, __shfl_xor(mx, 32));
;         float sum = 0.f;
; #pragma unroll
;         for (int r = 0; r < 10; ++r)
; #pragma unroll
;             for (int jj = 0; jj < 4; ++jj) { const float ev = __expf(acc[r][jj] - mx); acc[r][jj] = ev; sum += ev; }
;         sum += __shfl_xor(sum, 16); sum += __shfl_xor(sum, 32);
	v_fmamk_f32 v54, v54, 0x3e000000, v120
	v_cndmask_b32_e64 v61, v54, v236, s[42:43]
	v_fmamk_f32 v54, v55, 0x3e000000, v121
	v_cndmask_b32_e64 v68, v54, v236, s[42:43]
	v_fmamk_f32 v55, v56, 0x3e000000, v122
	v_mov_b32_e32 v89, v123
	v_fmac_f32_e32 v89, 0x3e000000, v57
	v_max3_f32 v54, v60, v61, v68
	v_cndmask_b32_e64 v60, v55, v236, s[42:43]
	v_cndmask_b32_e64 v69, v89, v236, s[42:43]
	v_max3_f32 v85, v54, v60, v69
	ds_read_b128 v[144:147], v84 offset:1088
	s_waitcnt lgkmcnt(5)
	v_fmamk_f32 v50, v50, 0x3e000000, v124
	v_cndmask_b32_e64 v54, v50, v236, s[44:45]
	v_fmamk_f32 v50, v51, 0x3e000000, v125
	v_cndmask_b32_e64 v55, v50, v236, s[44:45]
	v_fmamk_f32 v51, v52, 0x3e000000, v126
	v_mov_b32_e32 v57, v127
	v_fmac_f32_e32 v57, 0x3e000000, v53
	v_max3_f32 v50, v85, v54, v55
	v_cndmask_b32_e64 v56, v51, v236, s[44:45]
	v_cndmask_b32_e64 v57, v57, v236, s[44:45]
	v_max3_f32 v85, v50, v56, v57
	s_nop 0
	s_waitcnt lgkmcnt(4)
	v_fmamk_f32 v46, v46, 0x3e000000, v128
	v_cndmask_b32_e64 v86, v46, v236, s[44:45]
	v_fmamk_f32 v46, v47, 0x3e000000, v129
	v_cndmask_b32_e64 v51, v46, v236, s[44:45]
	v_fmamk_f32 v47, v48, 0x3e000000, v130
	v_mov_b32_e32 v53, v131
	v_fmac_f32_e32 v53, 0x3e000000, v49
	v_max3_f32 v46, v85, v86, v51
	v_cndmask_b32_e64 v52, v47, v236, s[44:45]
	v_cndmask_b32_e64 v53, v53, v236, s[44:45]
	v_max3_f32 v50, v46, v52, v53
	s_nop 0
	s_waitcnt lgkmcnt(3)
	v_fmamk_f32 v42, v42, 0x3e000000, v132
	v_cndmask_b32_e64 v85, v42, v236, s[44:45]
	v_fmamk_f32 v42, v43, 0x3e000000, v133
	v_cndmask_b32_e64 v87, v42, v236, s[44:45]
	v_fmamk_f32 v43, v44, 0x3e000000, v134
	v_mov_b32_e32 v49, v135
	v_fmac_f32_e32 v49, 0x3e000000, v45
	v_max3_f32 v42, v50, v85, v87
	v_cndmask_b32_e64 v48, v43, v236, s[44:45]
	v_cndmask_b32_e64 v88, v49, v236, s[44:45]
	v_max3_f32 v46, v42, v48, v88
	s_nop 0
	s_waitcnt lgkmcnt(2)
	v_fmamk_f32 v34, v34, 0x3e000000, v136
	v_cndmask_b32_e64 v89, v34, v236, s[44:45]
	v_fmamk_f32 v34, v35, 0x3e000000, v137
	v_cndmask_b32_e64 v90, v34, v236, s[44:45]
	v_fmamk_f32 v35, v36, 0x3e000000, v138
	v_mov_b32_e32 v45, v139
	v_fmac_f32_e32 v45, 0x3e000000, v37
	v_max3_f32 v34, v46, v89, v90
	v_cndmask_b32_e64 v91, v35, v236, s[44:45]
	v_cndmask_b32_e64 v92, v45, v236, s[44:45]
	v_max3_f32 v42, v34, v91, v92
	s_nop 0
	s_waitcnt lgkmcnt(1)
	v_fmamk_f32 v34, v30, 0x3e000000, v140
	v_fmamk_f32 v93, v31, 0x3e000000, v141
	v_max3_f32 v30, v42, v34, v93
	v_fmamk_f32 v94, v32, 0x3e000000, v142
	v_mov_b32_e32 v37, v143
	v_fmac_f32_e32 v37, 0x3e000000, v33
	v_max3_f32 v35, v30, v94, v37
	s_nop 0
	s_waitcnt lgkmcnt(0)
	v_fmamk_f32 v26, v26, 0x3e000000, v144
	s_waitcnt lgkmcnt(0)
	v_mov_b32_e32 v31, v145
	v_mov_b32_e32 v32, v146
	v_mov_b32_e32 v33, v147
	s_nop 1
	v_fmamk_f32 v84, v27, 0x3e000000, v31
	v_max3_f32 v27, v35, v26, v84
	v_fmamk_f32 v95, v28, 0x3e000000, v32
	v_fmac_f32_e32 v33, 0x3e000000, v29
	v_max3_f32 v27, v27, v95, v33
	ds_bpermute_b32 v28, v72, v27
	s_waitcnt lgkmcnt(0)
	v_max_f32_e32 v28, v28, v28
	v_max_f32_e32 v27, v27, v28
	ds_bpermute_b32 v28, v73, v27
	s_waitcnt lgkmcnt(0)
	v_max_f32_e32 v28, v28, v28
	v_max_f32_e32 v96, v27, v28
	v_sub_f32_e32 v28, v41, v96
	v_mul_f32_e32 v28, 0x3fb8aa3b, v28
	v_sub_f32_e32 v27, v66, v96
	v_exp_f32_e32 v66, v28
	v_sub_f32_e32 v28, v40, v96
	v_mul_f32_e32 v28, 0x3fb8aa3b, v28
	v_exp_f32_e32 v97, v28
	v_sub_f32_e32 v28, v38, v96
	v_mul_f32_e32 v28, 0x3fb8aa3b, v28
	v_exp_f32_e32 v98, v28
	v_sub_f32_e32 v28, v67, v96
	v_mul_f32_e32 v28, 0x3fb8aa3b, v28
	v_exp_f32_e32 v67, v28
	v_sub_f32_e32 v28, v63, v96
	v_mul_f32_e32 v28, 0x3fb8aa3b, v28
	v_exp_f32_e32 v63, v28
	v_sub_f32_e32 v28, v62, v96
	v_mul_f32_e32 v28, 0x3fb8aa3b, v28
	v_exp_f32_e32 v62, v28
	v_sub_f32_e32 v28, v39, v96
	v_mul_f32_e32 v28, 0x3fb8aa3b, v28
	v_exp_f32_e32 v99, v28
	v_sub_f32_e32 v28, v65, v96
	v_mul_f32_e32 v28, 0x3fb8aa3b, v28
	v_exp_f32_e32 v44, v28
	v_sub_f32_e32 v28, v64, v96
	v_mul_f32_e32 v28, 0x3fb8aa3b, v28
	v_exp_f32_e32 v46, v28
	v_sub_f32_e32 v28, v59, v96
	v_mul_f32_e32 v28, 0x3fb8aa3b, v28
	v_exp_f32_e32 v49, v28
	v_sub_f32_e32 v28, v58, v96
	v_mul_f32_e32 v28, 0x3fb8aa3b, v28
	v_exp_f32_e32 v59, v28
	v_sub_f32_e32 v28, v61, v96
	v_mul_f32_e32 v28, 0x3fb8aa3b, v28
	v_exp_f32_e32 v100, v28
	v_sub_f32_e32 v28, v68, v96
	v_mul_f32_e32 v28, 0x3fb8aa3b, v28
	v_exp_f32_e32 v68, v28
	v_sub_f32_e32 v28, v60, v96
	v_mul_f32_e32 v28, 0x3fb8aa3b, v28
	v_exp_f32_e32 v101, v28
	v_sub_f32_e32 v28, v69, v96
	v_mul_f32_e32 v28, 0x3fb8aa3b, v28
	v_mul_f32_e32 v27, 0x3fb8aa3b, v27
	v_exp_f32_e32 v69, v28
	v_sub_f32_e32 v28, v54, v96
	v_exp_f32_e32 v50, v27
	v_mul_f32_e32 v28, 0x3fb8aa3b, v28
	v_exp_f32_e32 v39, v28
	v_sub_f32_e32 v28, v55, v96
	v_mul_f32_e32 v28, 0x3fb8aa3b, v28
	v_exp_f32_e32 v40, v28
	v_sub_f32_e32 v28, v56, v96
	v_add_f32_e32 v27, 0, v50
	v_mul_f32_e32 v28, 0x3fb8aa3b, v28
	v_add_f32_e32 v27, v66, v27
	v_exp_f32_e32 v42, v28
	v_sub_f32_e32 v28, v57, v96
	v_add_f32_e32 v27, v97, v27
	v_mul_f32_e32 v28, 0x3fb8aa3b, v28
	v_add_f32_e32 v27, v98, v27
	v_exp_f32_e32 v47, v28
	v_sub_f32_e32 v28, v86, v96
	v_add_f32_e32 v27, v67, v27
	v_mul_f32_e32 v28, 0x3fb8aa3b, v28
	v_add_f32_e32 v27, v63, v27
	v_exp_f32_e32 v58, v28
	v_sub_f32_e32 v28, v51, v96
	v_add_f32_e32 v27, v62, v27
	v_mul_f32_e32 v28, 0x3fb8aa3b, v28
	v_add_f32_e32 v27, v99, v27
	v_exp_f32_e32 v102, v28
	v_sub_f32_e32 v28, v52, v96
	v_add_f32_e32 v27, v44, v27
	v_mul_f32_e32 v28, 0x3fb8aa3b, v28
	v_add_f32_e32 v27, v46, v27
	v_exp_f32_e32 v103, v28
	v_sub_f32_e32 v28, v53, v96
	v_add_f32_e32 v27, v49, v27
	v_mul_f32_e32 v28, 0x3fb8aa3b, v28
	v_add_f32_e32 v27, v59, v27
	v_exp_f32_e32 v104, v28
	v_sub_f32_e32 v28, v85, v96
	v_add_f32_e32 v27, v100, v27
; #define LAS __attribute__((address_space(3)))
; __device__ __forceinline__ unsigned pk2(float lo, float hi) { return pg8::cvt_pk_bf16(lo, hi); }
; #define MFMA16(a, b, c) __builtin_amdgcn_mfma_f32_16x16x32_bf16((a), (b), (c), 0, 0, 0)
; __device__ __forceinline__ void attn_item(int item, const float* const* in, int l, unsigned char* ws, bf16_t* ybuf, LAS unsigned char* lds, int tid, int lane, int wave) {
;     ...
; #pragma unroll
;         for (int r = 0; r < 10; ++r)
; #pragma unroll
;             for (int jj = 0; jj < 4; ++jj) { const float ev = __expf(acc[r][jj] - mx); acc[r][jj] = ev; sum += ev; }
;         sum += __shfl_xor(sum, 16); sum += __shfl_xor(sum, 32);
;         const float inv = 1.0f / (sum + __expf(sink - mx));
;         f32x4 o[4];
; #pragma unroll
;         for (int df = 0; df < 4; ++df) o[df] = (f32x4){0.f, 0.f, 0.f, 0.f};
; #pragma unroll
;         for (int s = 0; s < 5; ++s) {
;             u32x4v pw; pw.x = pk2(acc[2 * s][0], acc[2 * s][1]); pw.y = pk2(acc[2 * s][2], acc[2 * s][3]); pw.z = pk2(acc[2 * s + 1][0], acc[2 * s + 1][1]); pw.w = pk2(acc[2 * s + 1][2], acc[2 * s + 1][3]);
;             const bf16x8 P = __builtin_bit_cast(bf16x8, pw);
; #pragma unroll
;             for (int df = 0; df < 4; ++df) { const LAS bf16_t* vp = VT + (16 * df + fr) * 272 + 32 * (s_lo + s) + 4 * q;
;                 const u32x2v lo = *(const LAS u32x2v*)vp, hi = *(const LAS u32x2v*)(vp + 16);
;                 u32x4v aw; aw.x = lo.x; aw.y = lo.y; aw.z = hi.x; aw.w = hi.y;
;                 o[df] = MFMA16(__builtin_bit_cast(bf16x8, aw), P, o[df]); }
	v_mul_f32_e32 v28, 0x3fb8aa3b, v28
	v_add_f32_e32 v27, v68, v27
	v_exp_f32_e32 v35, v28
	v_sub_f32_e32 v28, v87, v96
	v_add_f32_e32 v27, v101, v27
	v_mul_f32_e32 v28, 0x3fb8aa3b, v28
	v_add_f32_e32 v27, v69, v27
	v_exp_f32_e32 v36, v28
	v_sub_f32_e32 v28, v48, v96
	v_add_f32_e32 v27, v39, v27
	v_mul_f32_e32 v28, 0x3fb8aa3b, v28
	v_add_f32_e32 v27, v40, v27
	v_exp_f32_e32 v38, v28
	v_sub_f32_e32 v28, v88, v96
	v_add_f32_e32 v27, v42, v27
	v_mul_f32_e32 v28, 0x3fb8aa3b, v28
	v_add_f32_e32 v27, v47, v27
	v_exp_f32_e32 v41, v28
	v_sub_f32_e32 v28, v89, v96
	v_add_f32_e32 v27, v58, v27
	v_mul_f32_e32 v28, 0x3fb8aa3b, v28
	v_add_f32_e32 v27, v102, v27
	v_exp_f32_e32 v43, v28
	v_sub_f32_e32 v28, v90, v96
	v_add_f32_e32 v27, v103, v27
	v_mul_f32_e32 v28, 0x3fb8aa3b, v28
	v_add_f32_e32 v27, v104, v27
	v_exp_f32_e32 v45, v28
	v_sub_f32_e32 v28, v91, v96
	v_add_f32_e32 v27, v35, v27
	v_mul_f32_e32 v28, 0x3fb8aa3b, v28
	v_add_f32_e32 v27, v36, v27
	v_exp_f32_e32 v48, v28
	v_sub_f32_e32 v28, v92, v96
	v_add_f32_e32 v27, v38, v27
	v_mul_f32_e32 v28, 0x3fb8aa3b, v28
	v_add_f32_e32 v27, v41, v27
	v_exp_f32_e32 v105, v28
	v_add_f32_e32 v27, v43, v27
	v_add_f32_e32 v27, v45, v27
	v_add_f32_e32 v27, v48, v27
	v_add_f32_e32 v28, v105, v27
	v_sub_f32_e32 v27, v34, v96
	v_mul_f32_e32 v27, 0x3fb8aa3b, v27
	v_exp_f32_e32 v27, v27
	v_sub_f32_e32 v26, v26, v96
	v_mul_f32_e32 v26, 0x3fb8aa3b, v26
	v_sub_f32_e32 v34, v95, v96
	v_add_f32_e32 v29, v27, v28
	v_sub_f32_e32 v28, v93, v96
	v_mul_f32_e32 v28, 0x3fb8aa3b, v28
	v_exp_f32_e32 v28, v28
	v_mul_f32_e32 v34, 0x3fb8aa3b, v34
	v_sub_f32_e32 v33, v33, v96
	v_exp_f32_e32 v34, v34
	v_add_f32_e32 v30, v28, v29
	v_sub_f32_e32 v29, v94, v96
	v_mul_f32_e32 v29, 0x3fb8aa3b, v29
	v_exp_f32_e32 v29, v29
	v_mul_f32_e32 v33, 0x3fb8aa3b, v33
	v_exp_f32_e32 v33, v33
	v_cvt_pk_bf16_f32 v54, v50, v66
	v_add_f32_e32 v31, v29, v30
	v_sub_f32_e32 v30, v37, v96
	v_mul_f32_e32 v30, 0x3fb8aa3b, v30
	v_exp_f32_e32 v30, v30
	v_cvt_pk_bf16_f32 v55, v97, v98
	v_cvt_pk_bf16_f32 v56, v67, v63
	v_cvt_pk_bf16_f32 v57, v62, v99
	s_nop 0
	v_add_f32_e32 v32, v30, v31
	v_exp_f32_e32 v31, v26
	s_nop 0
	v_add_f32_e32 v26, v31, v32
	v_sub_f32_e32 v32, v84, v96
	v_mul_f32_e32 v32, 0x3fb8aa3b, v32
	v_exp_f32_e32 v32, v32
	s_nop 0
	v_add_f32_e32 v26, v32, v26
	v_add_f32_e32 v26, v34, v26
	v_add_f32_e32 v26, v33, v26
	ds_bpermute_b32 v37, v72, v26
	s_waitcnt lgkmcnt(0)
	v_add_f32_e32 v26, v26, v37
	ds_bpermute_b32 v37, v73, v26
	s_waitcnt lgkmcnt(0)
	v_add_f32_e32 v26, v26, v37
	v_sub_f32_e32 v37, v74, v96
	v_mul_f32_e32 v37, 0x3fb8aa3b, v37
	v_exp_f32_e32 v37, v37
	s_nop 0
	v_add_f32_e32 v26, v37, v26
	v_mul_u32_u24_e32 v37, 0x220, v79
	v_add3_u32 v51, v83, s1, v37
	v_add_u32_e32 v50, 0x9000, v51
	v_add_u32_e32 v52, 0xb000, v51
	v_add_u32_e32 v53, 0xd000, v51
	v_add_u32_e32 v51, 0xf000, v51
	ds_read_b64 v[108:109], v50
	ds_read_b64 v[110:111], v50 offset:32
	ds_read_b64 v[112:113], v52 offset:512
	ds_read_b64 v[114:115], v52 offset:544
	ds_read_b64 v[116:117], v53 offset:1024
	ds_read_b64 v[118:119], v53 offset:1056
	ds_read_b64 v[120:121], v51 offset:1536
	ds_read_b64 v[122:123], v51 offset:1568
	s_nop 0
	s_nop 0
	s_nop 0
	s_or_b32 s1, s6, 1
	s_lshl_b32 s6, s1, 6
	v_add3_u32 v37, v83, s6, v37
	s_waitcnt lgkmcnt(6)
	v_mfma_f32_16x16x32_bf16 v[60:63], v[108:111], v[54:57], 0
	v_cvt_pk_bf16_f32 v92, v44, v46
	v_cvt_pk_bf16_f32 v93, v49, v59
	v_cvt_pk_bf16_f32 v94, v100, v68
	s_waitcnt lgkmcnt(4)
	v_mfma_f32_16x16x32_bf16 v[64:67], v[112:115], v[54:57], 0
	v_cvt_pk_bf16_f32 v95, v101, v69
	s_cmpk_gt_i32 s38, 0x1ff
	s_waitcnt lgkmcnt(2)
	v_mfma_f32_16x16x32_bf16 v[84:87], v[116:119], v[54:57], 0
	s_waitcnt lgkmcnt(0)
	v_mfma_f32_16x16x32_bf16 v[88:91], v[120:123], v[54:57], 0
	v_add_u32_e32 v57, 0x9000, v37
	ds_read2_b64 v[96:99], v57 offset1:4
	v_add_u32_e32 v55, 0xb000, v37
	s_waitcnt lgkmcnt(0)
	v_mfma_f32_16x16x32_bf16 v[60:63], v[96:99], v[92:95], v[60:63]
	ds_read2_b64 v[96:99], v55 offset0:64 offset1:68
	v_add_u32_e32 v56, 0xd000, v37
	v_add_u32_e32 v54, 0xf000, v37
	s_waitcnt lgkmcnt(0)
	v_mfma_f32_16x16x32_bf16 v[64:67], v[96:99], v[92:95], v[64:67]
	ds_read_b64 v[108:109], v56 offset:1024
	ds_read_b64 v[110:111], v56 offset:1056
	ds_read_b64 v[112:113], v54 offset:1536
	ds_read_b64 v[114:115], v54 offset:1568
	ds_read_b64 v[116:117], v50 offset:128
	ds_read_b64 v[118:119], v50 offset:160
	ds_read_b64 v[120:121], v52 offset:640
	ds_read_b64 v[122:123], v52 offset:672
	ds_read_b64 v[124:125], v53 offset:1152
	ds_read_b64 v[126:127], v53 offset:1184
	s_waitcnt lgkmcnt(8)
	v_mfma_f32_16x16x32_bf16 v[84:87], v[108:111], v[92:95], v[84:87]
	s_nop 0
	s_waitcnt lgkmcnt(6)
	v_mfma_f32_16x16x32_bf16 v[88:91], v[112:115], v[92:95], v[88:91]
	v_cvt_pk_bf16_f32 v92, v39, v40
	v_cvt_pk_bf16_f32 v93, v42, v47
	v_cvt_pk_bf16_f32 v94, v58, v102
	v_cvt_pk_bf16_f32 v95, v103, v104
	s_nop 0
	s_waitcnt lgkmcnt(4)
	v_mfma_f32_16x16x32_bf16 v[58:61], v[116:119], v[92:95], v[60:63]
	s_nop 0
	s_waitcnt lgkmcnt(2)
	v_mfma_f32_16x16x32_bf16 v[62:65], v[120:123], v[92:95], v[64:67]
	s_nop 2
	s_nop 0
	s_waitcnt lgkmcnt(0)
	s_waitcnt lgkmcnt(0)
	v_mov_b32_e32 v66, v124
	v_mov_b32_e32 v67, v125
	v_mov_b32_e32 v68, v126
	v_mov_b32_e32 v69, v127
	s_nop 1
	v_mfma_f32_16x16x32_bf16 v[66:69], v[66:69], v[92:95], v[84:87]
	s_nop 2
	ds_read_b64 v[108:109], v51 offset:1664
	ds_read_b64 v[110:111], v51 offset:1696
	ds_read_b64 v[112:113], v50 offset:192
	ds_read_b64 v[114:115], v50 offset:224
	ds_read_b64 v[116:117], v52 offset:704
	ds_read_b64 v[118:119], v52 offset:736
	ds_read_b64 v[120:121], v53 offset:1216
	ds_read_b64 v[122:123], v53 offset:1248
	ds_read_b64 v[124:125], v51 offset:1728
	ds_read_b64 v[126:127], v51 offset:1760
	ds_read_b64 v[128:129], v50 offset:256
	ds_read_b64 v[130:131], v50 offset:288
	v_cvt_pk_bf16_f32 v36, v35, v36
	v_cvt_pk_bf16_f32 v37, v38, v41
	v_cvt_pk_bf16_f32 v38, v43, v45
	v_cvt_pk_bf16_f32 v39, v48, v105
	ds_read_b64 v[132:133], v52 offset:768
	ds_read_b64 v[134:135], v52 offset:800
	ds_read_b64 v[136:137], v53 offset:1280
	ds_read_b64 v[138:139], v53 offset:1312
	s_waitcnt lgkmcnt(12)
; #define LAS __attribute__((address_space(3)))
; __device__ __forceinline__ unsigned pk2(float lo, float hi) { return pg8::cvt_pk_bf16(lo, hi); }
; #define MFMA16(a, b, c) __builtin_amdgcn_mfma_f32_16x16x32_bf16((a), (b), (c), 0, 0, 0)
; __device__ __forceinline__ void attn_item(int item, const float* const* in, int l, unsigned char* ws, bf16_t* ybuf, LAS unsigned char* lds, int tid, int lane, int wave) {
;     ...
;         for (int r = 0; r < 10; ++r) { const LAS bf16_t* kp = KL + (16 * (2 * s_lo + r) + fr) * 72 + 8 * q;
;             f32x4 a = (f32x4){0.f, 0.f, 0.f, 0.f}; a = MFMA16(*(const LAS bf16x8*)kp, Bq0, a); a = MFMA16(*(const LAS bf16x8*)(kp + 32), Bq1, a); acc[r] = a; }
;     ...
; #pragma unroll
;         for (int s = 0; s < 5; ++s) {
;             u32x4v pw; pw.x = pk2(acc[2 * s][0], acc[2 * s][1]); pw.y = pk2(acc[2 * s][2], acc[2 * s][3]); pw.z = pk2(acc[2 * s + 1][0], acc[2 * s + 1][1]); pw.w = pk2(acc[2 * s + 1][2], acc[2 * s + 1][3]);
;             const bf16x8 P = __builtin_bit_cast(bf16x8, pw);
; #pragma unroll
;             for (int df = 0; df < 4; ++df) { const LAS bf16_t* vp = VT + (16 * df + fr) * 272 + 32 * (s_lo + s) + 4 * q;
;                 const u32x2v lo = *(const LAS u32x2v*)vp, hi = *(const LAS u32x2v*)(vp + 16);
;                 u32x4v aw; aw.x = lo.x; aw.y = lo.y; aw.z = hi.x; aw.w = hi.y;
;                 o[df] = MFMA16(__builtin_bit_cast(bf16x8, aw), P, o[df]); }
;         }
; #pragma unroll
;         for (int df = 0; df < 4; ++df) { u32x2v w; w.x = pk2(o[df][0] * inv, o[df][1] * inv); w.y = pk2(o[df][2] * inv, o[df][3] * inv);
;             *(u32x2v*)(Y + gt * D + 256 + hq * 64 + 16 * df + 4 * q) = w; }
;     }
	v_mfma_f32_16x16x32_bf16 v[40:43], v[112:115], v[36:39], v[58:61]
	s_nop 2
	ds_read_b64 v[140:141], v51 offset:1792
	ds_read_b64 v[142:143], v51 offset:1824
	s_waitcnt lgkmcnt(12)
	v_mfma_f32_16x16x32_bf16 v[44:47], v[116:119], v[36:39], v[62:65]
	s_nop 2
	ds_read_b128 v[144:147], v81
	v_cvt_pk_bf16_f32 v28, v27, v28
	v_cvt_pk_bf16_f32 v29, v29, v30
	v_cvt_pk_bf16_f32 v30, v31, v32
	v_cvt_pk_bf16_f32 v31, v34, v33
	ds_read_b128 v[148:151], v81 offset:64
	s_waitcnt lgkmcnt(8)
	v_mfma_f32_16x16x32_bf16 v[32:35], v[128:131], v[28:31], v[40:43]
	s_nop 2
	ds_read_b128 v[152:155], v81 offset:18496
	v_div_scale_f32 v27, s[6:7], v26, v26, 1.0
	s_waitcnt lgkmcnt(7)
	v_mfma_f32_16x16x32_bf16 v[40:43], v[132:135], v[28:31], v[44:47]
	s_nop 2
	ds_read_b128 v[168:171], v81 offset:2368
	v_mfma_f32_16x16x32_bf16 v[58:61], v[120:123], v[36:39], v[66:69]
	s_waitcnt lgkmcnt(6)
	v_mfma_f32_16x16x32_bf16 v[44:47], v[136:139], v[28:31], v[58:61]
	s_nop 5
	ds_read_b128 v[172:175], v81 offset:2304
	v_mfma_f32_16x16x32_bf16 v[84:87], v[108:111], v[92:95], v[88:91]
	v_mfma_f32_16x16x32_bf16 v[36:39], v[124:127], v[36:39], v[84:87]
	s_waitcnt lgkmcnt(5)
	v_mfma_f32_16x16x32_bf16 v[28:31], v[140:143], v[28:31], v[36:39]
	v_or_b32_e32 v58, 16, v75
	s_nop 4
	v_rcp_f32_e32 v36, v27
	s_nop 0
	v_fma_f32 v37, -v27, v36, 1.0
	v_fmac_f32_e32 v36, v37, v36
	v_div_scale_f32 v37, vcc, 1.0, v26, 1.0
	v_mul_f32_e32 v38, v37, v36
	v_fma_f32 v39, -v27, v38, v37
	v_fmac_f32_e32 v38, v39, v36
	v_fma_f32 v27, -v27, v38, v37
	v_div_fmas_f32 v27, v27, v36, v38
	v_div_fixup_f32 v36, v27, v26, 1.0
	v_lshlrev_b64 v[26:27], 11, v[70:71]
	v_lshl_add_u64 v[26:27], s[64:65], 0, v[26:27]
	v_mul_f32_e32 v32, v32, v36
	v_mul_f32_e32 v33, v33, v36
	v_lshl_add_u64 v[26:27], v[26:27], 0, s[10:11]
	v_cvt_pk_bf16_f32 v32, v32, v33
	v_mul_f32_e32 v33, v34, v36
	v_lshl_add_u64 v[26:27], v[26:27], 0, v[0:1]
	v_mul_f32_e32 v34, v35, v36
	v_cvt_pk_bf16_f32 v33, v33, v34
	global_store_dwordx2 v[26:27], v[32:33], off offset:512
	v_mul_f32_e32 v32, v40, v36
	v_mul_f32_e32 v33, v41, v36
	v_cvt_pk_bf16_f32 v32, v32, v33
	v_mul_f32_e32 v33, v42, v36
	v_mul_f32_e32 v34, v43, v36
	v_cvt_pk_bf16_f32 v33, v33, v34
	global_store_dwordx2 v[26:27], v[32:33], off offset:544
	v_mul_f32_e32 v32, v44, v36
	v_mul_f32_e32 v33, v45, v36
	v_cvt_pk_bf16_f32 v32, v32, v33
	v_mul_f32_e32 v33, v46, v36
	v_mul_f32_e32 v28, v36, v28
	v_mul_f32_e32 v29, v36, v29
	v_mul_f32_e32 v34, v47, v36
	v_cvt_pk_bf16_f32 v33, v33, v34
	global_store_dwordx2 v[26:27], v[32:33], off offset:576
	v_cvt_pk_bf16_f32 v28, v28, v29
	v_mul_f32_e32 v29, v36, v30
	v_mul_f32_e32 v30, v36, v31
	v_cvt_pk_bf16_f32 v29, v29, v30
	global_store_dwordx2 v[26:27], v[28:29], off offset:608
	ds_read_b128 v[176:179], v81 offset:4672
	ds_read_b128 v[180:183], v81 offset:4608
	s_waitcnt lgkmcnt(6)
	v_mfma_f32_16x16x32_bf16 v[26:29], v[144:147], v[22:25], 0
	ds_read_b128 v[184:187], v81 offset:6976
	s_waitcnt lgkmcnt(6)
	v_mfma_f32_16x16x32_bf16 v[62:65], v[148:151], v[18:21], v[26:29]
	ds_read_b128 v[188:191], v81 offset:6912
	s_nop 3
	ds_read_b128 v[108:111], v81 offset:9280
	s_waitcnt lgkmcnt(5)
	v_mfma_f32_16x16x32_bf16 v[26:29], v[172:175], v[22:25], 0
	v_mfma_f32_16x16x32_bf16 v[84:87], v[168:171], v[18:21], v[26:29]
	ds_read_b128 v[112:115], v81 offset:9216
	s_nop 5
	ds_read_b128 v[116:119], v81 offset:11584
	s_waitcnt lgkmcnt(5)
	v_mfma_f32_16x16x32_bf16 v[26:29], v[180:183], v[22:25], 0
	v_mfma_f32_16x16x32_bf16 v[88:91], v[176:179], v[18:21], v[26:29]
	ds_read_b128 v[120:123], v81 offset:11520
	s_nop 5
	ds_read_b128 v[124:127], v81 offset:13888
	s_waitcnt lgkmcnt(5)
	v_mfma_f32_16x16x32_bf16 v[26:29], v[188:191], v[22:25], 0
	v_mfma_f32_16x16x32_bf16 v[46:49], v[184:187], v[18:21], v[26:29]
	ds_read_b128 v[128:131], v81 offset:13824
	s_nop 5
	ds_read_b128 v[132:135], v81 offset:16192
	s_waitcnt lgkmcnt(5)
	v_mfma_f32_16x16x32_bf16 v[26:29], v[112:115], v[22:25], 0
	v_mfma_f32_16x16x32_bf16 v[42:45], v[108:111], v[18:21], v[26:29]
	ds_read_b128 v[136:139], v81 offset:16128
	s_nop 5
	ds_read_b128 v[140:143], v81 offset:18432
	s_waitcnt lgkmcnt(5)
	v_mfma_f32_16x16x32_bf16 v[26:29], v[120:123], v[22:25], 0
	v_mfma_f32_16x16x32_bf16 v[38:41], v[116:119], v[18:21], v[26:29]
	ds_read_b128 v[144:147], v81 offset:20736
	s_nop 5
	ds_read_b128 v[148:151], v81 offset:20800
	s_waitcnt lgkmcnt(5)
	v_mfma_f32_16x16x32_bf16 v[26:29], v[128:131], v[22:25], 0
	v_mfma_f32_16x16x32_bf16 v[34:37], v[124:127], v[18:21], v[26:29]
	s_nop 0
	s_nop 5
	s_nop 0
	s_waitcnt lgkmcnt(3)
	v_mfma_f32_16x16x32_bf16 v[26:29], v[136:139], v[22:25], 0
	v_mfma_f32_16x16x32_bf16 v[30:33], v[132:135], v[18:21], v[26:29]
	s_nop 6
	s_nop 0
	s_waitcnt lgkmcnt(2)
	v_mfma_f32_16x16x32_bf16 v[26:29], v[140:143], v[22:25], 0
	v_mfma_f32_16x16x32_bf16 v[26:29], v[152:155], v[18:21], v[26:29]
	s_nop 0
	s_waitcnt lgkmcnt(1)
	v_mfma_f32_16x16x32_bf16 v[22:25], v[144:147], v[22:25], 0
	s_nop 0
	s_waitcnt lgkmcnt(0)
	v_mfma_f32_16x16x32_bf16 v[18:21], v[148:151], v[18:21], v[22:25]
	s_nop 4
	v_sub_u32_e32 v22, v58, v76
	v_lshrrev_b32_e32 v22, 2, v22
	v_sub_u32_e32 v22, v82, v22
	v_lshl_add_u32 v68, v22, 4, v77
	ds_read_b128 v[108:111], v68 offset:512
	ds_read_b128 v[112:115], v68 offset:576
	ds_read_b128 v[116:119], v68 offset:640
	s_waitcnt lgkmcnt(2)
	v_fmamk_f32 v22, v62, 0x3e000000, v108
	v_cndmask_b32_e64 v62, v22, v236, s[42:43]
	v_fmamk_f32 v22, v63, 0x3e000000, v109
	v_cndmask_b32_e64 v61, v22, v236, s[42:43]
	v_fmamk_f32 v23, v64, 0x3e000000, v110
	v_mov_b32_e32 v25, v111
	v_fmac_f32_e32 v25, 0x3e000000, v65
	v_max3_f32 v22, v74, v62, v61
	v_cndmask_b32_e64 v60, v23, v236, s[42:43]
	v_cndmask_b32_e64 v59, v25, v236, s[42:43]
	v_max3_f32 v63, v22, v60, v59
	s_nop 0
	s_waitcnt lgkmcnt(1)
; #define LAS __attribute__((address_space(3)))
; __device__ __forceinline__ void attn_item(int item, const float* const* in, int l, unsigned char* ws, bf16_t* ybuf, LAS unsigned char* lds, int tid, int lane, int wave) {
;     ...
;         float mx = sink;
; #pragma unroll
;         for (int r = 0; r < 10; ++r) { const f32x4 tb = *(const LAS f32x4*)(ct + 16 * r); const bool dead = (nb == 0) && (2 * s_lo + r < 8);
; #pragma unroll
;             for (int jj = 0; jj < 4; ++jj) { float sc = acc[r][jj] * 0.125f + tb[jj]; sc = dead ? NEG_INF : sc; acc[r][jj] = sc; mx = fmaxf(mx, sc); } }
;         mx = fmaxf(mx, __shfl_xor(mx, 16)); mx = fmaxf(mx, __shfl_xor(mx, 32));
;         float sum = 0.f;
; #pragma unroll
;         for (int r = 0; r < 10; ++r)
; #pragma unroll
;             for (int jj = 0; jj < 4; ++jj) { const float ev = __expf(acc[r][jj] - mx); acc[r][jj] = ev; sum += ev; }
	v_fmamk_f32 v22, v84, 0x3e000000, v112
	v_cndmask_b32_e64 v70, v22, v236, s[42:43]
	v_fmamk_f32 v22, v85, 0x3e000000, v113
	v_cndmask_b32_e64 v71, v22, v236, s[42:43]
	v_fmamk_f32 v23, v86, 0x3e000000, v114
	v_mov_b32_e32 v25, v115
	v_fmac_f32_e32 v25, 0x3e000000, v87
	v_max3_f32 v22, v63, v70, v71
	v_cndmask_b32_e64 v69, v23, v236, s[42:43]
	v_cndmask_b32_e64 v65, v25, v236, s[42:43]
	v_max3_f32 v63, v22, v69, v65
	s_nop 0
	s_waitcnt lgkmcnt(0)
	v_fmamk_f32 v22, v88, 0x3e000000, v116
	v_cndmask_b32_e64 v67, v22, v236, s[42:43]
	v_fmamk_f32 v22, v89, 0x3e000000, v117
	v_cndmask_b32_e64 v66, v22, v236, s[42:43]
	v_fmamk_f32 v23, v90, 0x3e000000, v118
	v_mov_b32_e32 v25, v119
	v_fmac_f32_e32 v25, 0x3e000000, v91
	v_max3_f32 v22, v63, v67, v66
	v_cndmask_b32_e64 v64, v23, v236, s[42:43]
	v_cndmask_b32_e64 v63, v25, v236, s[42:43]
	v_max3_f32 v81, v22, v64, v63
	ds_read_b128 v[22:25], v68 offset:704
	s_waitcnt lgkmcnt(0)
	v_fmamk_f32 v22, v46, 0x3e000000, v22
	v_cndmask_b32_e64 v46, v22, v236, s[42:43]
	v_fmamk_f32 v22, v47, 0x3e000000, v23
	v_cndmask_b32_e64 v82, v22, v236, s[42:43]
	v_fmamk_f32 v23, v48, 0x3e000000, v24
	v_fmac_f32_e32 v25, 0x3e000000, v49
	v_max3_f32 v22, v81, v46, v82
	v_cndmask_b32_e64 v48, v23, v236, s[42:43]
	v_cndmask_b32_e64 v81, v25, v236, s[42:43]
	v_max3_f32 v47, v22, v48, v81
	ds_read_b128 v[108:111], v68 offset:768
	ds_read_b128 v[112:115], v68 offset:832
	ds_read_b128 v[116:119], v68 offset:896
	ds_read_b128 v[120:123], v68 offset:960
	ds_read_b128 v[124:127], v68 offset:1024
	ds_read_b128 v[128:131], v68 offset:1088
	s_waitcnt lgkmcnt(5)
	v_fmamk_f32 v22, v42, 0x3e000000, v108
	v_cndmask_b32_e64 v42, v22, v236, s[44:45]
	v_fmamk_f32 v22, v43, 0x3e000000, v109
	v_cndmask_b32_e64 v43, v22, v236, s[44:45]
	v_fmamk_f32 v23, v44, 0x3e000000, v110
	v_mov_b32_e32 v25, v111
	v_fmac_f32_e32 v25, 0x3e000000, v45
	v_max3_f32 v22, v47, v42, v43
	v_cndmask_b32_e64 v44, v23, v236, s[44:45]
	v_cndmask_b32_e64 v83, v25, v236, s[44:45]
	v_max3_f32 v45, v22, v44, v83
	s_nop 0
	s_waitcnt lgkmcnt(4)
	v_fmamk_f32 v22, v38, 0x3e000000, v112
	v_cndmask_b32_e64 v84, v22, v236, s[44:45]
	v_fmamk_f32 v22, v39, 0x3e000000, v113
	v_cndmask_b32_e64 v85, v22, v236, s[44:45]
	v_fmamk_f32 v23, v40, 0x3e000000, v114
	v_mov_b32_e32 v25, v115
	v_fmac_f32_e32 v25, 0x3e000000, v41
	v_max3_f32 v22, v45, v84, v85
	v_cndmask_b32_e64 v40, v23, v236, s[44:45]
	v_cndmask_b32_e64 v86, v25, v236, s[44:45]
	v_max3_f32 v38, v22, v40, v86
	s_nop 0
	s_waitcnt lgkmcnt(3)
	v_fmamk_f32 v22, v34, 0x3e000000, v116
	v_cndmask_b32_e64 v87, v22, v236, s[44:45]
	v_fmamk_f32 v22, v35, 0x3e000000, v117
	v_cndmask_b32_e64 v35, v22, v236, s[44:45]
	v_fmamk_f32 v23, v36, 0x3e000000, v118
	v_mov_b32_e32 v25, v119
	v_fmac_f32_e32 v25, 0x3e000000, v37
	v_max3_f32 v22, v38, v87, v35
	v_cndmask_b32_e64 v88, v23, v236, s[44:45]
	v_cndmask_b32_e64 v37, v25, v236, s[44:45]
	v_max3_f32 v34, v22, v88, v37
	s_nop 0
	s_waitcnt lgkmcnt(2)
	v_fmamk_f32 v22, v30, 0x3e000000, v120
	v_cndmask_b32_e64 v89, v22, v236, s[44:45]
	v_fmamk_f32 v22, v31, 0x3e000000, v121
	v_cndmask_b32_e64 v90, v22, v236, s[44:45]
	v_fmamk_f32 v23, v32, 0x3e000000, v122
	v_mov_b32_e32 v25, v123
	v_fmac_f32_e32 v25, 0x3e000000, v33
	v_max3_f32 v22, v34, v89, v90
	v_cndmask_b32_e64 v91, v23, v236, s[44:45]
	v_cndmask_b32_e64 v92, v25, v236, s[44:45]
	v_max3_f32 v30, v22, v91, v92
	s_nop 0
	s_waitcnt lgkmcnt(1)
	v_fmamk_f32 v22, v26, 0x3e000000, v124
	v_fmamk_f32 v23, v27, 0x3e000000, v125
	v_max3_f32 v26, v30, v22, v23
	v_fmamk_f32 v24, v28, 0x3e000000, v126
	v_mov_b32_e32 v25, v127
	v_fmac_f32_e32 v25, 0x3e000000, v29
	v_max3_f32 v30, v26, v24, v25
	s_nop 0
	s_waitcnt lgkmcnt(0)
	v_fmamk_f32 v18, v18, 0x3e000000, v128
	v_fmamk_f32 v26, v19, 0x3e000000, v129
	v_max3_f32 v19, v30, v18, v26
	s_waitcnt lgkmcnt(0)
	v_mov_b32_e32 v28, v130
	v_mov_b32_e32 v29, v131
	s_nop 1
	v_fmamk_f32 v68, v20, 0x3e000000, v28
	v_fmac_f32_e32 v29, 0x3e000000, v21
	v_max3_f32 v19, v19, v68, v29
	ds_bpermute_b32 v20, v72, v19
	s_waitcnt lgkmcnt(0)
	v_max_f32_e32 v20, v20, v20
	v_max_f32_e32 v19, v19, v20
	ds_bpermute_b32 v20, v73, v19
	s_waitcnt lgkmcnt(0)
	v_max_f32_e32 v20, v20, v20
	v_max_f32_e32 v93, v19, v20
	v_sub_f32_e32 v20, v61, v93
	v_mul_f32_e32 v20, 0x3fb8aa3b, v20
	v_exp_f32_e32 v47, v20
	v_sub_f32_e32 v20, v60, v93
	v_mul_f32_e32 v20, 0x3fb8aa3b, v20
	v_exp_f32_e32 v60, v20
	v_sub_f32_e32 v20, v59, v93
	v_mul_f32_e32 v20, 0x3fb8aa3b, v20
	v_exp_f32_e32 v94, v20
	v_sub_f32_e32 v20, v70, v93
	v_mul_f32_e32 v20, 0x3fb8aa3b, v20
	v_exp_f32_e32 v70, v20
	v_sub_f32_e32 v20, v71, v93
	v_mul_f32_e32 v20, 0x3fb8aa3b, v20
	v_exp_f32_e32 v71, v20
	v_sub_f32_e32 v20, v69, v93
	v_mul_f32_e32 v20, 0x3fb8aa3b, v20
	v_exp_f32_e32 v69, v20
	v_sub_f32_e32 v20, v65, v93
	v_mul_f32_e32 v20, 0x3fb8aa3b, v20
	v_exp_f32_e32 v65, v20
	v_sub_f32_e32 v20, v67, v93
	v_mul_f32_e32 v20, 0x3fb8aa3b, v20
	v_exp_f32_e32 v36, v20
	v_sub_f32_e32 v20, v66, v93
	v_mul_f32_e32 v20, 0x3fb8aa3b, v20
	v_exp_f32_e32 v38, v20
	v_sub_f32_e32 v20, v64, v93
	v_mul_f32_e32 v20, 0x3fb8aa3b, v20
	v_exp_f32_e32 v41, v20
	v_sub_f32_e32 v20, v63, v93
	v_mul_f32_e32 v20, 0x3fb8aa3b, v20
	v_exp_f32_e32 v49, v20
	v_sub_f32_e32 v20, v46, v93
	v_mul_f32_e32 v20, 0x3fb8aa3b, v20
	v_exp_f32_e32 v61, v20
	v_sub_f32_e32 v20, v82, v93
	v_mul_f32_e32 v20, 0x3fb8aa3b, v20
	v_exp_f32_e32 v95, v20
	v_sub_f32_e32 v20, v48, v93
	v_mul_f32_e32 v20, 0x3fb8aa3b, v20
	v_exp_f32_e32 v96, v20
	v_sub_f32_e32 v20, v81, v93
	v_sub_f32_e32 v19, v62, v93
	v_mul_f32_e32 v20, 0x3fb8aa3b, v20
	v_mul_f32_e32 v19, 0x3fb8aa3b, v19
	v_exp_f32_e32 v81, v20
	v_sub_f32_e32 v20, v42, v93
	v_exp_f32_e32 v45, v19
; #define LAS __attribute__((address_space(3)))
; __device__ __forceinline__ unsigned pk2(float lo, float hi) { return pg8::cvt_pk_bf16(lo, hi); }
; #define MFMA16(a, b, c) __builtin_amdgcn_mfma_f32_16x16x32_bf16((a), (b), (c), 0, 0, 0)
; __device__ __forceinline__ void attn_item(int item, const float* const* in, int l, unsigned char* ws, bf16_t* ybuf, LAS unsigned char* lds, int tid, int lane, int wave) {
;     ...
; #pragma unroll
;         for (int r = 0; r < 10; ++r)
; #pragma unroll
;             for (int jj = 0; jj < 4; ++jj) { const float ev = __expf(acc[r][jj] - mx); acc[r][jj] = ev; sum += ev; }
;         sum += __shfl_xor(sum, 16); sum += __shfl_xor(sum, 32);
;         const float inv = 1.0f / (sum + __expf(sink - mx));
;         f32x4 o[4];
; #pragma unroll
;         for (int df = 0; df < 4; ++df) o[df] = (f32x4){0.f, 0.f, 0.f, 0.f};
; #pragma unroll
;         for (int s = 0; s < 5; ++s) {
;             u32x4v pw; pw.x = pk2(acc[2 * s][0], acc[2 * s][1]); pw.y = pk2(acc[2 * s][2], acc[2 * s][3]); pw.z = pk2(acc[2 * s + 1][0], acc[2 * s + 1][1]); pw.w = pk2(acc[2 * s + 1][2], acc[2 * s + 1][3]);
;             const bf16x8 P = __builtin_bit_cast(bf16x8, pw);
; #pragma unroll
;             for (int df = 0; df < 4; ++df) { const LAS bf16_t* vp = VT + (16 * df + fr) * 272 + 32 * (s_lo + s) + 4 * q;
;                 const u32x2v lo = *(const LAS u32x2v*)vp, hi = *(const LAS u32x2v*)(vp + 16);
;                 u32x4v aw; aw.x = lo.x; aw.y = lo.y; aw.z = hi.x; aw.w = hi.y;
;                 o[df] = MFMA16(__builtin_bit_cast(bf16x8, aw), P, o[df]); }
	v_mul_f32_e32 v20, 0x3fb8aa3b, v20
	v_exp_f32_e32 v31, v20
	v_sub_f32_e32 v20, v43, v93
	v_mul_f32_e32 v20, 0x3fb8aa3b, v20
	v_exp_f32_e32 v32, v20
	v_sub_f32_e32 v20, v44, v93
	v_add_f32_e32 v19, 0, v45
	v_mul_f32_e32 v20, 0x3fb8aa3b, v20
	v_add_f32_e32 v19, v47, v19
	v_exp_f32_e32 v34, v20
	v_sub_f32_e32 v20, v83, v93
	v_add_f32_e32 v19, v60, v19
	v_mul_f32_e32 v20, 0x3fb8aa3b, v20
	v_add_f32_e32 v19, v94, v19
	v_exp_f32_e32 v39, v20
	v_sub_f32_e32 v20, v84, v93
	v_add_f32_e32 v19, v70, v19
	v_mul_f32_e32 v20, 0x3fb8aa3b, v20
	v_add_f32_e32 v19, v71, v19
	v_exp_f32_e32 v44, v20
	v_sub_f32_e32 v20, v85, v93
	v_add_f32_e32 v19, v69, v19
	v_mul_f32_e32 v20, 0x3fb8aa3b, v20
	v_add_f32_e32 v19, v65, v19
	v_exp_f32_e32 v46, v20
	v_sub_f32_e32 v20, v40, v93
	v_add_f32_e32 v19, v36, v19
	v_mul_f32_e32 v20, 0x3fb8aa3b, v20
	v_add_f32_e32 v19, v38, v19
	v_exp_f32_e32 v59, v20
	v_sub_f32_e32 v20, v86, v93
	v_add_f32_e32 v19, v41, v19
	v_mul_f32_e32 v20, 0x3fb8aa3b, v20
	v_add_f32_e32 v19, v49, v19
	v_exp_f32_e32 v98, v20
	v_sub_f32_e32 v20, v87, v93
	v_add_f32_e32 v19, v61, v19
	v_mul_f32_e32 v20, 0x3fb8aa3b, v20
	v_add_f32_e32 v19, v95, v19
	v_exp_f32_e32 v27, v20
	v_sub_f32_e32 v20, v35, v93
	v_add_f32_e32 v19, v96, v19
	v_mul_f32_e32 v20, 0x3fb8aa3b, v20
	v_add_f32_e32 v19, v81, v19
	v_exp_f32_e32 v28, v20
	v_sub_f32_e32 v20, v88, v93
	v_add_f32_e32 v19, v31, v19
	v_mul_f32_e32 v20, 0x3fb8aa3b, v20
	v_add_f32_e32 v19, v32, v19
	v_exp_f32_e32 v30, v20
	v_sub_f32_e32 v20, v37, v93
	v_add_f32_e32 v19, v34, v19
	v_mul_f32_e32 v20, 0x3fb8aa3b, v20
	v_add_f32_e32 v19, v39, v19
	v_exp_f32_e32 v33, v20
	v_sub_f32_e32 v20, v89, v93
	v_add_f32_e32 v19, v44, v19
	v_mul_f32_e32 v20, 0x3fb8aa3b, v20
	v_add_f32_e32 v19, v46, v19
	v_exp_f32_e32 v35, v20
	v_sub_f32_e32 v20, v90, v93
	v_add_f32_e32 v19, v59, v19
	v_mul_f32_e32 v20, 0x3fb8aa3b, v20
	v_add_f32_e32 v19, v98, v19
	v_exp_f32_e32 v37, v20
	v_sub_f32_e32 v20, v91, v93
	v_add_f32_e32 v19, v27, v19
	v_mul_f32_e32 v20, 0x3fb8aa3b, v20
	v_add_f32_e32 v19, v28, v19
	v_exp_f32_e32 v40, v20
	v_sub_f32_e32 v20, v92, v93
	v_add_f32_e32 v19, v30, v19
	v_mul_f32_e32 v20, 0x3fb8aa3b, v20
	v_add_f32_e32 v19, v33, v19
	v_exp_f32_e32 v48, v20
	v_add_f32_e32 v19, v35, v19
	v_add_f32_e32 v19, v37, v19
	v_add_f32_e32 v19, v40, v19
	v_add_f32_e32 v20, v48, v19
	v_sub_f32_e32 v19, v22, v93
	v_mul_f32_e32 v19, 0x3fb8aa3b, v19
	v_exp_f32_e32 v19, v19
	v_sub_f32_e32 v18, v18, v93
	v_mul_f32_e32 v18, 0x3fb8aa3b, v18
	v_cvt_pk_bf16_f32 v62, v45, v47
	v_add_f32_e32 v21, v19, v20
	v_sub_f32_e32 v20, v23, v93
	v_mul_f32_e32 v20, 0x3fb8aa3b, v20
	v_exp_f32_e32 v20, v20
	v_cvt_pk_bf16_f32 v63, v60, v94
	v_cvt_pk_bf16_f32 v64, v70, v71
	v_cvt_pk_bf16_f32 v65, v69, v65
	ds_read_b64 v[108:109], v52 offset:512
	ds_read_b64 v[110:111], v52 offset:544
	ds_read_b64 v[112:113], v53 offset:1024
	ds_read_b64 v[114:115], v53 offset:1056
	ds_read_b64 v[116:117], v50
	ds_read_b64 v[118:119], v50 offset:32
	v_add_f32_e32 v22, v20, v21
	v_sub_f32_e32 v21, v24, v93
	v_mul_f32_e32 v21, 0x3fb8aa3b, v21
	v_exp_f32_e32 v21, v21
	s_nop 0
	s_waitcnt lgkmcnt(4)
	v_mfma_f32_16x16x32_bf16 v[82:85], v[108:111], v[62:65], 0
	v_add_f32_e32 v23, v21, v22
	v_sub_f32_e32 v22, v25, v93
	v_mul_f32_e32 v22, 0x3fb8aa3b, v22
	v_exp_f32_e32 v22, v22
	v_sub_f32_e32 v25, v68, v93
	v_mul_f32_e32 v25, 0x3fb8aa3b, v25
	v_exp_f32_e32 v25, v25
	v_add_f32_e32 v24, v22, v23
	v_exp_f32_e32 v23, v18
	s_nop 0
	s_waitcnt lgkmcnt(0)
	v_mfma_f32_16x16x32_bf16 v[66:69], v[116:119], v[62:65], 0
	v_add_f32_e32 v18, v23, v24
	v_sub_f32_e32 v24, v26, v93
	v_mul_f32_e32 v24, 0x3fb8aa3b, v24
	v_exp_f32_e32 v24, v24
	v_sub_f32_e32 v26, v29, v93
	v_mul_f32_e32 v26, 0x3fb8aa3b, v26
	v_exp_f32_e32 v26, v26
	v_add_f32_e32 v18, v24, v18
	v_add_f32_e32 v18, v25, v18
	v_mfma_f32_16x16x32_bf16 v[86:89], v[112:115], v[62:65], 0
	v_add_f32_e32 v18, v26, v18
	ds_bpermute_b32 v29, v72, v18
	v_or_b32_e32 v42, s0, v58
	v_mov_b32_e32 v43, s13
	s_waitcnt lgkmcnt(0)
	v_add_f32_e32 v18, v18, v29
	ds_bpermute_b32 v29, v73, v18
	s_waitcnt lgkmcnt(0)
	v_add_f32_e32 v18, v18, v29
	v_sub_f32_e32 v29, v74, v93
	ds_read_b64 v[108:109], v51 offset:1536
	ds_read_b64 v[110:111], v51 offset:1568
	ds_read_b64 v[112:113], v57
	ds_read_b64 v[114:115], v57 offset:32
	ds_read_b64 v[116:117], v55 offset:512
	ds_read_b64 v[118:119], v55 offset:544
	ds_read_b64 v[120:121], v56 offset:1024
	ds_read_b64 v[122:123], v56 offset:1056
	ds_read_b64 v[124:125], v54 offset:1536
	ds_read_b64 v[126:127], v54 offset:1568
	ds_read_b64 v[128:129], v50 offset:128
	ds_read_b64 v[130:131], v50 offset:160
	s_waitcnt lgkmcnt(10)
	v_mfma_f32_16x16x32_bf16 v[62:65], v[108:111], v[62:65], 0
	v_cvt_pk_bf16_f32 v90, v36, v38
	v_cvt_pk_bf16_f32 v91, v41, v49
	v_cvt_pk_bf16_f32 v92, v61, v95
	v_cvt_pk_bf16_f32 v93, v96, v81
	s_nop 0
	s_waitcnt lgkmcnt(8)
	v_mfma_f32_16x16x32_bf16 v[66:69], v[112:115], v[90:93], v[66:69]
	s_nop 0
	v_mul_f32_e32 v29, 0x3fb8aa3b, v29
	v_exp_f32_e32 v29, v29
	s_waitcnt lgkmcnt(6)
	v_mfma_f32_16x16x32_bf16 v[82:85], v[116:119], v[90:93], v[82:85]
	s_nop 0
	v_add_f32_e32 v18, v29, v18
	s_waitcnt lgkmcnt(4)
	v_mfma_f32_16x16x32_bf16 v[86:89], v[120:123], v[90:93], v[86:89]
	s_nop 0
	s_waitcnt lgkmcnt(2)
	v_mfma_f32_16x16x32_bf16 v[60:63], v[124:127], v[90:93], v[62:65]
	v_cvt_pk_bf16_f32 v90, v31, v32
	v_cvt_pk_bf16_f32 v91, v34, v39
	v_cvt_pk_bf16_f32 v92, v44, v46
	v_cvt_pk_bf16_f32 v93, v59, v98
	s_nop 0
	s_waitcnt lgkmcnt(0)
	s_waitcnt lgkmcnt(0)
; #define LAS __attribute__((address_space(3)))
; __device__ __forceinline__ unsigned pk2(float lo, float hi) { return pg8::cvt_pk_bf16(lo, hi); }
; #define MFMA16(a, b, c) __builtin_amdgcn_mfma_f32_16x16x32_bf16((a), (b), (c), 0, 0, 0)
; __device__ __forceinline__ void attn_item(int item, const float* const* in, int l, unsigned char* ws, bf16_t* ybuf, LAS unsigned char* lds, int tid, int lane, int wave) {
;     ...
;         for (int r = 0; r < 10; ++r) { const LAS bf16_t* kp = KL + (16 * (2 * s_lo + r) + fr) * 72 + 8 * q;
;             f32x4 a = (f32x4){0.f, 0.f, 0.f, 0.f}; a = MFMA16(*(const LAS bf16x8*)kp, Bq0, a); a = MFMA16(*(const LAS bf16x8*)(kp + 32), Bq1, a); acc[r] = a; }
;     ...
; #pragma unroll
;         for (int s = 0; s < 5; ++s) {
;             u32x4v pw; pw.x = pk2(acc[2 * s][0], acc[2 * s][1]); pw.y = pk2(acc[2 * s][2], acc[2 * s][3]); pw.z = pk2(acc[2 * s + 1][0], acc[2 * s + 1][1]); pw.w = pk2(acc[2 * s + 1][2], acc[2 * s + 1][3]);
;             const bf16x8 P = __builtin_bit_cast(bf16x8, pw);
; #pragma unroll
;             for (int df = 0; df < 4; ++df) { const LAS bf16_t* vp = VT + (16 * df + fr) * 272 + 32 * (s_lo + s) + 4 * q;
;                 const u32x2v lo = *(const LAS u32x2v*)vp, hi = *(const LAS u32x2v*)(vp + 16);
;                 u32x4v aw; aw.x = lo.x; aw.y = lo.y; aw.z = hi.x; aw.w = hi.y;
;                 o[df] = MFMA16(__builtin_bit_cast(bf16x8, aw), P, o[df]); }
;         }
; #pragma unroll
;         for (int df = 0; df < 4; ++df) { u32x2v w; w.x = pk2(o[df][0] * inv, o[df][1] * inv); w.y = pk2(o[df][2] * inv, o[df][3] * inv);
;             *(u32x2v*)(Y + gt * D + 256 + hq * 64 + 16 * df + 4 * q) = w; }
;     }
	v_mov_b32_e32 v44, v128
	v_mov_b32_e32 v45, v129
	v_mov_b32_e32 v46, v130
	v_mov_b32_e32 v47, v131
	s_nop 1
	v_mfma_f32_16x16x32_bf16 v[44:47], v[44:47], v[90:93], v[66:69]
	s_nop 2
	ds_read_b64 v[108:109], v52 offset:640
	ds_read_b64 v[110:111], v52 offset:672
	ds_read_b64 v[112:113], v53 offset:1152
	ds_read_b64 v[114:115], v53 offset:1184
	ds_read_b64 v[116:117], v51 offset:1664
	ds_read_b64 v[118:119], v51 offset:1696
	ds_read_b64 v[120:121], v50 offset:192
	ds_read_b64 v[122:123], v50 offset:224
	ds_read_b64 v[124:125], v52 offset:704
	ds_read_b64 v[126:127], v52 offset:736
	ds_read_b64 v[128:129], v53 offset:1216
	ds_read_b64 v[130:131], v53 offset:1248
	ds_read_b64 v[132:133], v51 offset:1728
	ds_read_b64 v[134:135], v51 offset:1760
	s_waitcnt lgkmcnt(12)
	v_mfma_f32_16x16x32_bf16 v[64:67], v[108:111], v[90:93], v[82:85]
	s_nop 2
	ds_read_b64 v[136:137], v50 offset:256
	ds_read_b64 v[138:139], v50 offset:288
	v_cvt_pk_bf16_f32 v28, v27, v28
	v_cvt_pk_bf16_f32 v29, v30, v33
	v_cvt_pk_bf16_f32 v30, v35, v37
	v_cvt_pk_bf16_f32 v31, v40, v48
	ds_read_b64 v[140:141], v52 offset:768
	ds_read_b64 v[142:143], v52 offset:800
	ds_read_b64 v[144:145], v53 offset:1280
	ds_read_b64 v[146:147], v53 offset:1312
	s_waitcnt lgkmcnt(14)
	v_mfma_f32_16x16x32_bf16 v[58:61], v[116:119], v[90:93], v[60:63]
	s_waitcnt lgkmcnt(12)
	v_mfma_f32_16x16x32_bf16 v[32:35], v[120:123], v[28:31], v[44:47]
	s_nop 2
	s_nop 0
	s_waitcnt lgkmcnt(10)
	v_mfma_f32_16x16x32_bf16 v[36:39], v[124:127], v[28:31], v[64:67]
	s_nop 2
	s_nop 0
	v_cvt_pk_bf16_f32 v20, v19, v20
	v_cvt_pk_bf16_f32 v21, v21, v22
	v_cvt_pk_bf16_f32 v22, v23, v24
	v_cvt_pk_bf16_f32 v23, v25, v26
	s_nop 0
	s_waitcnt lgkmcnt(4)
	v_mfma_f32_16x16x32_bf16 v[24:27], v[136:139], v[20:23], v[32:35]
	s_nop 2
	s_nop 0
	v_div_scale_f32 v19, s[6:7], v18, v18, 1.0
	s_waitcnt lgkmcnt(2)
	v_mfma_f32_16x16x32_bf16 v[32:35], v[140:143], v[20:23], v[36:39]
	s_nop 2
	s_nop 0
	s_waitcnt lgkmcnt(0)
	v_mov_b32_e32 v36, v144
	v_mov_b32_e32 v37, v145
	v_mov_b32_e32 v38, v146
	v_mov_b32_e32 v39, v147
	v_mov_b32_e32 v44, v128
	v_mov_b32_e32 v45, v129
	v_mov_b32_e32 v46, v130
	v_mov_b32_e32 v47, v131
	v_mov_b32_e32 v62, v132
	v_mov_b32_e32 v63, v133
	v_mov_b32_e32 v64, v134
	v_mov_b32_e32 v65, v135
	v_mov_b32_e32 v68, v112
	v_mov_b32_e32 v69, v113
	v_mov_b32_e32 v70, v114
	v_mov_b32_e32 v71, v115
	s_nop 1
	v_mfma_f32_16x16x32_bf16 v[68:71], v[68:71], v[90:93], v[86:89]
	v_mfma_f32_16x16x32_bf16 v[44:47], v[44:47], v[28:31], v[68:71]
	s_waitcnt lgkmcnt(0)
	v_mfma_f32_16x16x32_bf16 v[36:39], v[36:39], v[20:23], v[44:47]
	v_mfma_f32_16x16x32_bf16 v[28:31], v[62:65], v[28:31], v[58:61]
	s_nop 4
	ds_read2_b64 v[44:47], v51 offset0:224 offset1:228
	s_waitcnt lgkmcnt(0)
	v_mfma_f32_16x16x32_bf16 v[20:23], v[44:47], v[20:23], v[28:31]
	s_nop 2
	v_rcp_f32_e32 v28, v19
	v_lshl_or_b32 v45, s1, 3, v78
	v_fma_f32 v29, -v19, v28, 1.0
	v_fmac_f32_e32 v28, v29, v28
	v_div_scale_f32 v29, vcc, 1.0, v18, 1.0
	v_mul_f32_e32 v30, v29, v28
	v_fma_f32 v31, -v19, v30, v29
	v_fmac_f32_e32 v30, v31, v28
	v_fma_f32 v19, -v19, v30, v29
	v_div_fmas_f32 v19, v19, v28, v30
	v_div_fixup_f32 v28, v19, v18, 1.0
	v_lshlrev_b64 v[18:19], 11, v[42:43]
	v_lshl_add_u64 v[18:19], s[64:65], 0, v[18:19]
	v_mul_f32_e32 v24, v24, v28
	v_mul_f32_e32 v25, v25, v28
	v_lshl_add_u64 v[18:19], v[18:19], 0, s[10:11]
	v_cvt_pk_bf16_f32 v24, v24, v25
	v_mul_f32_e32 v25, v26, v28
	v_lshl_add_u64 v[18:19], v[18:19], 0, v[0:1]
	v_mul_f32_e32 v26, v27, v28
	v_cvt_pk_bf16_f32 v25, v25, v26
	global_store_dwordx2 v[18:19], v[24:25], off offset:512
	v_mul_f32_e32 v24, v32, v28
	v_mul_f32_e32 v25, v33, v28
	v_cvt_pk_bf16_f32 v24, v24, v25
	v_mul_f32_e32 v25, v34, v28
	v_mul_f32_e32 v26, v35, v28
	v_cvt_pk_bf16_f32 v25, v25, v26
	global_store_dwordx2 v[18:19], v[24:25], off offset:544
	v_mul_f32_e32 v24, v36, v28
	v_mul_f32_e32 v25, v37, v28
	v_cvt_pk_bf16_f32 v24, v24, v25
	v_mul_f32_e32 v25, v38, v28
	v_mul_f32_e32 v20, v28, v20
	v_mul_f32_e32 v21, v28, v21
	v_mul_f32_e32 v26, v39, v28
	v_cvt_pk_bf16_f32 v25, v25, v26
	global_store_dwordx2 v[18:19], v[24:25], off offset:576
	v_cvt_pk_bf16_f32 v20, v20, v21
	v_mul_f32_e32 v21, v28, v22
	v_mul_f32_e32 v22, v28, v23
	v_cvt_pk_bf16_f32 v21, v21, v22
	global_store_dwordx2 v[18:19], v[20:21], off offset:608
	v_lshl_or_b32 v18, s1, 5, v79
	v_mad_u32_u24 v44, v18, s39, v80
	ds_read_b128 v[108:111], v44
	ds_read_b128 v[112:115], v44 offset:64
	ds_read_b128 v[116:119], v44 offset:18496
	ds_read_b128 v[120:123], v44 offset:2368
	ds_read_b128 v[124:127], v44 offset:2304
	ds_read_b128 v[128:131], v44 offset:4672
	ds_read_b128 v[132:135], v44 offset:4608
	s_waitcnt lgkmcnt(6)
	v_mfma_f32_16x16x32_bf16 v[18:21], v[108:111], v[14:17], 0
	ds_read_b128 v[136:139], v44 offset:6976
	v_or_b32_e32 v42, 32, v75
	s_waitcnt lgkmcnt(6)
	v_mfma_f32_16x16x32_bf16 v[58:61], v[112:115], v[10:13], v[18:21]
	ds_read_b128 v[140:143], v44 offset:6912
	s_nop 2
	ds_read_b128 v[144:147], v44 offset:9280
	s_waitcnt lgkmcnt(5)
	v_mfma_f32_16x16x32_bf16 v[18:21], v[124:127], v[14:17], 0
	v_mfma_f32_16x16x32_bf16 v[62:65], v[120:123], v[10:13], v[18:21]
	ds_read_b128 v[148:151], v44 offset:9216
	s_nop 5
	ds_read_b128 v[152:155], v44 offset:11584
	s_waitcnt lgkmcnt(5)
	v_mfma_f32_16x16x32_bf16 v[18:21], v[132:135], v[14:17], 0
	v_mfma_f32_16x16x32_bf16 v[66:69], v[128:131], v[10:13], v[18:21]
	ds_read_b128 v[168:171], v44 offset:11520
	s_nop 5
	ds_read_b128 v[172:175], v44 offset:13888
	s_waitcnt lgkmcnt(5)
	v_mfma_f32_16x16x32_bf16 v[18:21], v[140:143], v[14:17], 0
	v_mfma_f32_16x16x32_bf16 v[38:41], v[136:139], v[10:13], v[18:21]
	ds_read_b128 v[176:179], v44 offset:13824
	s_nop 5
	ds_read_b128 v[180:183], v44 offset:16192
	s_waitcnt lgkmcnt(5)
; #define LAS __attribute__((address_space(3)))
; #define MFMA16(a, b, c) __builtin_amdgcn_mfma_f32_16x16x32_bf16((a), (b), (c), 0, 0, 0)
; __device__ __forceinline__ void attn_item(int item, const float* const* in, int l, unsigned char* ws, bf16_t* ybuf, LAS unsigned char* lds, int tid, int lane, int wave) {
;     ...
;         for (int r = 0; r < 10; ++r) { const LAS bf16_t* kp = KL + (16 * (2 * s_lo + r) + fr) * 72 + 8 * q;
;             f32x4 a = (f32x4){0.f, 0.f, 0.f, 0.f}; a = MFMA16(*(const LAS bf16x8*)kp, Bq0, a); a = MFMA16(*(const LAS bf16x8*)(kp + 32), Bq1, a); acc[r] = a; }
;         const int a1 = iq + 1, sft = (4 - (a1 & 3)) & 3, a4 = (a1 + sft) >> 2;
;         const LAS float* ct = CT + (hl * 4 + sft) * 384 + 128 + 4 * (4 * (2 * s_lo) + q - a4);
;         float mx = sink;
; #pragma unroll
;         for (int r = 0; r < 10; ++r) { const f32x4 tb = *(const LAS f32x4*)(ct + 16 * r); const bool dead = (nb == 0) && (2 * s_lo + r < 8);
; #pragma unroll
;             for (int jj = 0; jj < 4; ++jj) { float sc = acc[r][jj] * 0.125f + tb[jj]; sc = dead ? NEG_INF : sc; acc[r][jj] = sc; mx = fmaxf(mx, sc); } }
;         mx = fmaxf(mx, __shfl_xor(mx, 16)); mx = fmaxf(mx, __shfl_xor(mx, 32));
	v_mfma_f32_16x16x32_bf16 v[18:21], v[148:151], v[14:17], 0
	v_mfma_f32_16x16x32_bf16 v[34:37], v[144:147], v[10:13], v[18:21]
	ds_read_b128 v[184:187], v44 offset:16128
	s_nop 5
	ds_read_b128 v[188:191], v44 offset:18432
	s_waitcnt lgkmcnt(5)
	v_mfma_f32_16x16x32_bf16 v[18:21], v[168:171], v[14:17], 0
	v_mfma_f32_16x16x32_bf16 v[30:33], v[152:155], v[10:13], v[18:21]
	ds_read_b128 v[108:111], v44 offset:20736
	s_nop 5
	ds_read_b128 v[112:115], v44 offset:20800
	s_waitcnt lgkmcnt(5)
	v_mfma_f32_16x16x32_bf16 v[18:21], v[176:179], v[14:17], 0
	v_mfma_f32_16x16x32_bf16 v[26:29], v[172:175], v[10:13], v[18:21]
	s_nop 0
	s_nop 5
	s_nop 0
	s_waitcnt lgkmcnt(3)
	v_mfma_f32_16x16x32_bf16 v[18:21], v[184:187], v[14:17], 0
	v_mfma_f32_16x16x32_bf16 v[22:25], v[180:183], v[10:13], v[18:21]
	s_nop 6
	s_nop 0
	s_waitcnt lgkmcnt(2)
	v_mfma_f32_16x16x32_bf16 v[18:21], v[188:191], v[14:17], 0
	v_mfma_f32_16x16x32_bf16 v[18:21], v[116:119], v[10:13], v[18:21]
	s_nop 0
	s_waitcnt lgkmcnt(1)
	v_mfma_f32_16x16x32_bf16 v[14:17], v[108:111], v[14:17], 0
	s_nop 0
	s_waitcnt lgkmcnt(0)
	v_mfma_f32_16x16x32_bf16 v[10:13], v[112:115], v[10:13], v[14:17]
	s_nop 4
	v_sub_u32_e32 v14, v42, v76
	v_lshrrev_b32_e32 v14, 2, v14
	v_sub_u32_e32 v14, v45, v14
	v_lshl_add_u32 v70, v14, 4, v77
	ds_read_b128 v[108:111], v70 offset:512
	ds_read_b128 v[112:115], v70 offset:576
	ds_read_b128 v[116:119], v70 offset:640
	ds_read_b128 v[120:123], v70 offset:704
	ds_read_b128 v[124:127], v70 offset:768
	ds_read_b128 v[128:131], v70 offset:832
	v_or_b32_e32 v42, s0, v42
	s_waitcnt lgkmcnt(5)
	v_fmamk_f32 v14, v58, 0x3e000000, v108
	v_cndmask_b32_e64 v49, v14, v236, s[42:43]
	v_fmamk_f32 v14, v59, 0x3e000000, v109
	v_cndmask_b32_e64 v48, v14, v236, s[42:43]
	v_fmamk_f32 v15, v60, 0x3e000000, v110
	v_mov_b32_e32 v17, v111
	v_fmac_f32_e32 v17, 0x3e000000, v61
	v_max3_f32 v14, v74, v49, v48
	v_cndmask_b32_e64 v47, v15, v236, s[42:43]
	v_cndmask_b32_e64 v46, v17, v236, s[42:43]
	v_max3_f32 v58, v14, v47, v46
	ds_read_b128 v[132:135], v70 offset:896
	s_waitcnt lgkmcnt(5)
	v_fmamk_f32 v14, v62, 0x3e000000, v112
	v_cndmask_b32_e64 v59, v14, v236, s[42:43]
	v_fmamk_f32 v14, v63, 0x3e000000, v113
	v_cndmask_b32_e64 v60, v14, v236, s[42:43]
	v_fmamk_f32 v15, v64, 0x3e000000, v114
	v_mov_b32_e32 v17, v115
	v_fmac_f32_e32 v17, 0x3e000000, v65
	v_max3_f32 v14, v58, v59, v60
	v_cndmask_b32_e64 v58, v15, v236, s[42:43]
	v_cndmask_b32_e64 v61, v17, v236, s[42:43]
	v_max3_f32 v62, v14, v58, v61
	ds_read_b128 v[136:139], v70 offset:960
	s_waitcnt lgkmcnt(5)
	v_fmamk_f32 v14, v66, 0x3e000000, v116
	v_cndmask_b32_e64 v63, v14, v236, s[44:45]
	v_fmamk_f32 v14, v67, 0x3e000000, v117
	v_cndmask_b32_e64 v64, v14, v236, s[44:45]
	v_fmamk_f32 v15, v68, 0x3e000000, v118
	v_mov_b32_e32 v17, v119
	v_fmac_f32_e32 v17, 0x3e000000, v69
	v_max3_f32 v14, v62, v63, v64
	v_cndmask_b32_e64 v62, v15, v236, s[44:45]
	v_cndmask_b32_e64 v65, v17, v236, s[44:45]
	v_max3_f32 v66, v14, v62, v65
	ds_read_b128 v[140:143], v70 offset:1024
	s_waitcnt lgkmcnt(5)
	v_fmamk_f32 v14, v38, 0x3e000000, v120
	v_cndmask_b32_e64 v38, v14, v236, s[44:45]
	v_fmamk_f32 v14, v39, 0x3e000000, v121
	v_cndmask_b32_e64 v67, v14, v236, s[44:45]
	v_fmamk_f32 v15, v40, 0x3e000000, v122
	v_mov_b32_e32 v17, v123
	v_fmac_f32_e32 v17, 0x3e000000, v41
	v_max3_f32 v14, v66, v38, v67
	v_cndmask_b32_e64 v66, v15, v236, s[44:45]
	v_cndmask_b32_e64 v41, v17, v236, s[44:45]
	v_max3_f32 v39, v14, v66, v41
	ds_read_b128 v[144:147], v70 offset:1088
	s_waitcnt lgkmcnt(5)
	v_fmamk_f32 v14, v34, 0x3e000000, v124
	v_cndmask_b32_e64 v34, v14, v236, s[44:45]
	v_fmamk_f32 v14, v35, 0x3e000000, v125
	v_cndmask_b32_e64 v68, v14, v236, s[44:45]
	v_fmamk_f32 v15, v36, 0x3e000000, v126
	v_mov_b32_e32 v17, v127
	v_fmac_f32_e32 v17, 0x3e000000, v37
	v_max3_f32 v14, v39, v34, v68
	v_cndmask_b32_e64 v36, v15, v236, s[44:45]
	v_cndmask_b32_e64 v69, v17, v236, s[44:45]
	v_max3_f32 v35, v14, v36, v69
	s_nop 0
	s_waitcnt lgkmcnt(4)
	v_fmamk_f32 v14, v30, 0x3e000000, v128
	v_cndmask_b32_e64 v71, v14, v236, s[44:45]
	v_fmamk_f32 v14, v31, 0x3e000000, v129
	v_cndmask_b32_e64 v31, v14, v236, s[44:45]
	v_fmamk_f32 v15, v32, 0x3e000000, v130
	v_mov_b32_e32 v17, v131
	v_fmac_f32_e32 v17, 0x3e000000, v33
	v_max3_f32 v14, v35, v71, v31
	v_cndmask_b32_e64 v78, v15, v236, s[44:45]
	v_cndmask_b32_e64 v79, v17, v236, s[44:45]
	v_max3_f32 v30, v14, v78, v79
	s_nop 0
	s_waitcnt lgkmcnt(3)
	v_fmamk_f32 v14, v26, 0x3e000000, v132
	v_fmamk_f32 v15, v27, 0x3e000000, v133
	v_max3_f32 v26, v30, v14, v15
	v_fmamk_f32 v16, v28, 0x3e000000, v134
	v_mov_b32_e32 v17, v135
	v_fmac_f32_e32 v17, 0x3e000000, v29
	v_max3_f32 v30, v26, v16, v17
	s_nop 0
	s_waitcnt lgkmcnt(2)
	v_fmamk_f32 v80, v22, 0x3e000000, v136
	v_fmamk_f32 v81, v23, 0x3e000000, v137
	v_max3_f32 v22, v30, v80, v81
	v_fmamk_f32 v82, v24, 0x3e000000, v138
	v_mov_b32_e32 v29, v139
	v_fmac_f32_e32 v29, 0x3e000000, v25
	v_max3_f32 v26, v22, v82, v29
	s_nop 0
	s_waitcnt lgkmcnt(1)
	v_fmamk_f32 v83, v18, 0x3e000000, v140
	v_fmamk_f32 v84, v19, 0x3e000000, v141
	v_max3_f32 v18, v26, v83, v84
	v_fmamk_f32 v85, v20, 0x3e000000, v142
	v_mov_b32_e32 v25, v143
	v_fmac_f32_e32 v25, 0x3e000000, v21
	v_max3_f32 v22, v18, v85, v25
	s_nop 0
	s_waitcnt lgkmcnt(0)
	v_fmamk_f32 v10, v10, 0x3e000000, v144
	v_fmamk_f32 v18, v11, 0x3e000000, v145
	v_max3_f32 v11, v22, v10, v18
	s_waitcnt lgkmcnt(0)
	v_mov_b32_e32 v20, v146
	v_mov_b32_e32 v21, v147
	s_nop 1
	v_fmamk_f32 v70, v12, 0x3e000000, v20
	v_fmac_f32_e32 v21, 0x3e000000, v13
	v_max3_f32 v11, v11, v70, v21
	ds_bpermute_b32 v12, v72, v11
	s_waitcnt lgkmcnt(0)
; #define LAS __attribute__((address_space(3)))
; __device__ __forceinline__ unsigned pk2(float lo, float hi) { return pg8::cvt_pk_bf16(lo, hi); }
; #define MFMA16(a, b, c) __builtin_amdgcn_mfma_f32_16x16x32_bf16((a), (b), (c), 0, 0, 0)
; __device__ __forceinline__ void attn_item(int item, const float* const* in, int l, unsigned char* ws, bf16_t* ybuf, LAS unsigned char* lds, int tid, int lane, int wave) {
;     ...
; #pragma unroll
;         for (int r = 0; r < 10; ++r)
; #pragma unroll
;             for (int jj = 0; jj < 4; ++jj) { const float ev = __expf(acc[r][jj] - mx); acc[r][jj] = ev; sum += ev; }
;         sum += __shfl_xor(sum, 16); sum += __shfl_xor(sum, 32);
;         const float inv = 1.0f / (sum + __expf(sink - mx));
;         f32x4 o[4];
; #pragma unroll
;         for (int df = 0; df < 4; ++df) o[df] = (f32x4){0.f, 0.f, 0.f, 0.f};
; #pragma unroll
;         for (int s = 0; s < 5; ++s) {
;             u32x4v pw; pw.x = pk2(acc[2 * s][0], acc[2 * s][1]); pw.y = pk2(acc[2 * s][2], acc[2 * s][3]); pw.z = pk2(acc[2 * s + 1][0], acc[2 * s + 1][1]); pw.w = pk2(acc[2 * s + 1][2], acc[2 * s + 1][3]);
;             const bf16x8 P = __builtin_bit_cast(bf16x8, pw);
; #pragma unroll
;             for (int df = 0; df < 4; ++df) { const LAS bf16_t* vp = VT + (16 * df + fr) * 272 + 32 * (s_lo + s) + 4 * q;
;                 const u32x2v lo = *(const LAS u32x2v*)vp, hi = *(const LAS u32x2v*)(vp + 16);
;                 u32x4v aw; aw.x = lo.x; aw.y = lo.y; aw.z = hi.x; aw.w = hi.y;
;                 o[df] = MFMA16(__builtin_bit_cast(bf16x8, aw), P, o[df]); }
	v_max_f32_e32 v12, v12, v12
	v_max_f32_e32 v11, v11, v12
	ds_bpermute_b32 v12, v73, v11
	s_waitcnt lgkmcnt(0)
	v_max_f32_e32 v12, v12, v12
	v_max_f32_e32 v86, v11, v12
	v_sub_f32_e32 v12, v48, v86
	v_mul_f32_e32 v12, 0x3fb8aa3b, v12
	v_exp_f32_e32 v39, v12
	v_sub_f32_e32 v12, v47, v86
	v_mul_f32_e32 v12, 0x3fb8aa3b, v12
	v_exp_f32_e32 v47, v12
	v_sub_f32_e32 v12, v46, v86
	v_mul_f32_e32 v12, 0x3fb8aa3b, v12
	v_exp_f32_e32 v48, v12
	v_sub_f32_e32 v12, v59, v86
	v_mul_f32_e32 v12, 0x3fb8aa3b, v12
	v_sub_f32_e32 v11, v49, v86
	v_exp_f32_e32 v49, v12
	v_sub_f32_e32 v12, v60, v86
	v_mul_f32_e32 v12, 0x3fb8aa3b, v12
	v_exp_f32_e32 v60, v12
	v_sub_f32_e32 v12, v58, v86
	v_mul_f32_e32 v12, 0x3fb8aa3b, v12
	v_exp_f32_e32 v87, v12
	v_sub_f32_e32 v12, v61, v86
	v_mul_f32_e32 v12, 0x3fb8aa3b, v12
	v_exp_f32_e32 v61, v12
	v_sub_f32_e32 v12, v63, v86
	v_mul_f32_e32 v12, 0x3fb8aa3b, v12
	v_exp_f32_e32 v30, v12
	v_sub_f32_e32 v12, v64, v86
	v_mul_f32_e32 v12, 0x3fb8aa3b, v12
	v_exp_f32_e32 v32, v12
	v_sub_f32_e32 v12, v62, v86
	v_mul_f32_e32 v12, 0x3fb8aa3b, v12
	v_exp_f32_e32 v35, v12
	v_sub_f32_e32 v12, v65, v86
	v_mul_f32_e32 v12, 0x3fb8aa3b, v12
	v_exp_f32_e32 v40, v12
	v_sub_f32_e32 v12, v38, v86
	v_mul_f32_e32 v12, 0x3fb8aa3b, v12
	v_exp_f32_e32 v46, v12
	v_sub_f32_e32 v12, v67, v86
	v_mul_f32_e32 v12, 0x3fb8aa3b, v12
	v_exp_f32_e32 v88, v12
	v_sub_f32_e32 v12, v66, v86
	v_mul_f32_e32 v12, 0x3fb8aa3b, v12
	v_exp_f32_e32 v89, v12
	v_sub_f32_e32 v12, v41, v86
	v_mul_f32_e32 v12, 0x3fb8aa3b, v12
	v_mul_f32_e32 v11, 0x3fb8aa3b, v11
	v_exp_f32_e32 v90, v12
	v_sub_f32_e32 v12, v34, v86
	v_exp_f32_e32 v37, v11
	v_mul_f32_e32 v12, 0x3fb8aa3b, v12
	v_exp_f32_e32 v23, v12
	v_sub_f32_e32 v12, v68, v86
	v_mul_f32_e32 v12, 0x3fb8aa3b, v12
	v_exp_f32_e32 v24, v12
	v_sub_f32_e32 v12, v36, v86
	v_add_f32_e32 v11, 0, v37
	v_mul_f32_e32 v12, 0x3fb8aa3b, v12
	v_add_f32_e32 v11, v39, v11
	v_exp_f32_e32 v27, v12
	v_sub_f32_e32 v12, v69, v86
	v_add_f32_e32 v11, v47, v11
	v_mul_f32_e32 v12, 0x3fb8aa3b, v12
	v_add_f32_e32 v11, v48, v11
	v_exp_f32_e32 v33, v12
	v_sub_f32_e32 v12, v71, v86
	v_add_f32_e32 v11, v49, v11
	v_mul_f32_e32 v12, 0x3fb8aa3b, v12
	v_add_f32_e32 v11, v60, v11
	v_exp_f32_e32 v36, v12
	v_sub_f32_e32 v12, v31, v86
	v_add_f32_e32 v11, v87, v11
	v_mul_f32_e32 v12, 0x3fb8aa3b, v12
	v_add_f32_e32 v11, v61, v11
	v_exp_f32_e32 v38, v12
	v_sub_f32_e32 v12, v78, v86
	v_add_f32_e32 v11, v30, v11
	v_mul_f32_e32 v12, 0x3fb8aa3b, v12
	v_add_f32_e32 v11, v32, v11
	v_exp_f32_e32 v41, v12
	v_sub_f32_e32 v12, v79, v86
	v_add_f32_e32 v11, v35, v11
	v_mul_f32_e32 v12, 0x3fb8aa3b, v12
	v_add_f32_e32 v11, v40, v11
	v_exp_f32_e32 v71, v12
	v_sub_f32_e32 v12, v14, v86
	v_add_f32_e32 v11, v46, v11
	v_mul_f32_e32 v12, 0x3fb8aa3b, v12
	v_add_f32_e32 v11, v88, v11
	v_exp_f32_e32 v19, v12
	v_sub_f32_e32 v12, v15, v86
	v_add_f32_e32 v11, v89, v11
	v_mul_f32_e32 v12, 0x3fb8aa3b, v12
	v_add_f32_e32 v11, v90, v11
	v_exp_f32_e32 v20, v12
	v_sub_f32_e32 v12, v16, v86
	v_add_f32_e32 v11, v23, v11
	v_mul_f32_e32 v12, 0x3fb8aa3b, v12
	v_add_f32_e32 v11, v24, v11
	v_exp_f32_e32 v22, v12
	v_sub_f32_e32 v12, v17, v86
	v_add_f32_e32 v11, v27, v11
	v_mul_f32_e32 v12, 0x3fb8aa3b, v12
	v_add_f32_e32 v11, v33, v11
	v_exp_f32_e32 v26, v12
	v_sub_f32_e32 v12, v80, v86
	v_add_f32_e32 v11, v36, v11
	v_mul_f32_e32 v12, 0x3fb8aa3b, v12
	v_add_f32_e32 v11, v38, v11
	v_exp_f32_e32 v28, v12
	v_sub_f32_e32 v12, v81, v86
	v_add_f32_e32 v11, v41, v11
	v_mul_f32_e32 v12, 0x3fb8aa3b, v12
	v_add_f32_e32 v11, v71, v11
	v_exp_f32_e32 v31, v12
	v_sub_f32_e32 v12, v82, v86
	v_add_f32_e32 v11, v19, v11
	v_mul_f32_e32 v12, 0x3fb8aa3b, v12
	v_add_f32_e32 v11, v20, v11
	v_exp_f32_e32 v34, v12
	v_sub_f32_e32 v12, v29, v86
	v_add_f32_e32 v11, v22, v11
	v_mul_f32_e32 v12, 0x3fb8aa3b, v12
	v_add_f32_e32 v11, v26, v11
	v_exp_f32_e32 v29, v12
	v_add_f32_e32 v11, v28, v11
	v_add_f32_e32 v11, v31, v11
	v_add_f32_e32 v11, v34, v11
	v_add_f32_e32 v12, v29, v11
	v_sub_f32_e32 v11, v83, v86
	v_mul_f32_e32 v11, 0x3fb8aa3b, v11
	v_exp_f32_e32 v11, v11
	v_cvt_pk_bf16_f32 v58, v37, v39
	v_cvt_pk_bf16_f32 v59, v47, v48
	v_cvt_pk_bf16_f32 v60, v49, v60
	v_cvt_pk_bf16_f32 v61, v87, v61
	ds_read_b64 v[108:109], v57
	ds_read_b64 v[110:111], v57 offset:32
	ds_read_b64 v[112:113], v55 offset:512
	ds_read_b64 v[114:115], v55 offset:544
	ds_read_b64 v[116:117], v56 offset:1024
	ds_read_b64 v[118:119], v56 offset:1056
	ds_read_b64 v[120:121], v54 offset:1536
	ds_read_b64 v[122:123], v54 offset:1568
	ds_read_b64 v[124:125], v50 offset:128
	ds_read_b64 v[126:127], v50 offset:160
	ds_read_b64 v[128:129], v52 offset:640
	ds_read_b64 v[130:131], v52 offset:672
	v_add_f32_e32 v13, v11, v12
	v_sub_f32_e32 v12, v84, v86
	v_mul_f32_e32 v12, 0x3fb8aa3b, v12
	v_exp_f32_e32 v12, v12
	ds_read_b64 v[132:133], v53 offset:1152
	ds_read_b64 v[134:135], v53 offset:1184
	ds_read_b64 v[136:137], v51 offset:1664
	ds_read_b64 v[138:139], v51 offset:1696
	s_waitcnt lgkmcnt(14)
	v_mfma_f32_16x16x32_bf16 v[62:65], v[108:111], v[58:61], 0
	v_add_f32_e32 v14, v12, v13
	v_sub_f32_e32 v13, v85, v86
	ds_read_b64 v[140:141], v50 offset:192
	ds_read_b64 v[142:143], v50 offset:224
	s_waitcnt lgkmcnt(14)
	v_mfma_f32_16x16x32_bf16 v[66:69], v[112:115], v[58:61], 0
	v_mul_f32_e32 v13, 0x3fb8aa3b, v13
	v_exp_f32_e32 v13, v13
	v_sub_f32_e32 v10, v10, v86
	s_waitcnt lgkmcnt(12)
	v_mfma_f32_16x16x32_bf16 v[78:81], v[116:119], v[58:61], 0
	v_mul_f32_e32 v10, 0x3fb8aa3b, v10
	v_add_f32_e32 v15, v13, v14
	v_sub_f32_e32 v14, v25, v86
	s_waitcnt lgkmcnt(10)
	v_mfma_f32_16x16x32_bf16 v[58:61], v[120:123], v[58:61], 0
	v_cvt_pk_bf16_f32 v82, v30, v32
	v_cvt_pk_bf16_f32 v83, v35, v40
	v_cvt_pk_bf16_f32 v84, v46, v88
	v_cvt_pk_bf16_f32 v85, v89, v90
	s_nop 0
	s_waitcnt lgkmcnt(8)
; #define LAS __attribute__((address_space(3)))
; __device__ __forceinline__ unsigned pk2(float lo, float hi) { return pg8::cvt_pk_bf16(lo, hi); }
; #define MFMA16(a, b, c) __builtin_amdgcn_mfma_f32_16x16x32_bf16((a), (b), (c), 0, 0, 0)
; __device__ __forceinline__ void attn_item(int item, const float* const* in, int l, unsigned char* ws, bf16_t* ybuf, LAS unsigned char* lds, int tid, int lane, int wave) {
;     ...
;         for (int r = 0; r < 10; ++r) { const LAS bf16_t* kp = KL + (16 * (2 * s_lo + r) + fr) * 72 + 8 * q;
;             f32x4 a = (f32x4){0.f, 0.f, 0.f, 0.f}; a = MFMA16(*(const LAS bf16x8*)kp, Bq0, a); a = MFMA16(*(const LAS bf16x8*)(kp + 32), Bq1, a); acc[r] = a; }
;     ...
; #pragma unroll
;         for (int s = 0; s < 5; ++s) {
;             u32x4v pw; pw.x = pk2(acc[2 * s][0], acc[2 * s][1]); pw.y = pk2(acc[2 * s][2], acc[2 * s][3]); pw.z = pk2(acc[2 * s + 1][0], acc[2 * s + 1][1]); pw.w = pk2(acc[2 * s + 1][2], acc[2 * s + 1][3]);
;             const bf16x8 P = __builtin_bit_cast(bf16x8, pw);
; #pragma unroll
;             for (int df = 0; df < 4; ++df) { const LAS bf16_t* vp = VT + (16 * df + fr) * 272 + 32 * (s_lo + s) + 4 * q;
;                 const u32x2v lo = *(const LAS u32x2v*)vp, hi = *(const LAS u32x2v*)(vp + 16);
;                 u32x4v aw; aw.x = lo.x; aw.y = lo.y; aw.z = hi.x; aw.w = hi.y;
;                 o[df] = MFMA16(__builtin_bit_cast(bf16x8, aw), P, o[df]); }
;         }
; #pragma unroll
;         for (int df = 0; df < 4; ++df) { u32x2v w; w.x = pk2(o[df][0] * inv, o[df][1] * inv); w.y = pk2(o[df][2] * inv, o[df][3] * inv);
;             *(u32x2v*)(Y + gt * D + 256 + hq * 64 + 16 * df + 4 * q) = w; }
;     }
	v_mfma_f32_16x16x32_bf16 v[46:49], v[124:127], v[82:85], v[62:65]
	s_nop 2
	s_nop 0
	v_mul_f32_e32 v14, 0x3fb8aa3b, v14
	v_exp_f32_e32 v14, v14
	s_waitcnt lgkmcnt(6)
	v_mfma_f32_16x16x32_bf16 v[62:65], v[128:131], v[82:85], v[66:69]
	s_nop 2
	s_nop 0
	v_add_f32_e32 v16, v14, v15
	v_exp_f32_e32 v15, v10
	s_waitcnt lgkmcnt(4)
	v_mfma_f32_16x16x32_bf16 v[66:69], v[132:135], v[82:85], v[78:81]
	s_nop 2
	s_nop 0
	v_add_f32_e32 v10, v15, v16
	v_sub_f32_e32 v16, v18, v86
	s_waitcnt lgkmcnt(2)
	v_mfma_f32_16x16x32_bf16 v[58:61], v[136:139], v[82:85], v[58:61]
	v_cvt_pk_bf16_f32 v78, v23, v24
	v_cvt_pk_bf16_f32 v79, v27, v33
	v_cvt_pk_bf16_f32 v80, v36, v38
	v_cvt_pk_bf16_f32 v81, v41, v71
	s_nop 0
	v_mul_f32_e32 v16, 0x3fb8aa3b, v16
	v_sub_f32_e32 v17, v70, v86
	v_exp_f32_e32 v16, v16
	v_mul_f32_e32 v17, 0x3fb8aa3b, v17
	v_sub_f32_e32 v18, v21, v86
	v_exp_f32_e32 v17, v17
	v_mul_f32_e32 v18, 0x3fb8aa3b, v18
	v_exp_f32_e32 v18, v18
	v_add_f32_e32 v10, v16, v10
	v_add_f32_e32 v10, v17, v10
	s_waitcnt lgkmcnt(0)
	v_mfma_f32_16x16x32_bf16 v[36:39], v[140:143], v[78:81], v[46:49]
	v_add_f32_e32 v10, v18, v10
	ds_bpermute_b32 v21, v72, v10
	s_waitcnt lgkmcnt(0)
	v_add_f32_e32 v10, v10, v21
	ds_read2_b64 v[46:49], v52 offset0:88 offset1:92
	ds_bpermute_b32 v21, v73, v10
	s_waitcnt lgkmcnt(1)
	v_mfma_f32_16x16x32_bf16 v[46:49], v[46:49], v[78:81], v[62:65]
	s_nop 2
	ds_read_b64 v[108:109], v53 offset:1216
	ds_read_b64 v[110:111], v53 offset:1248
	ds_read_b64 v[112:113], v51 offset:1728
	ds_read_b64 v[114:115], v51 offset:1760
	ds_read_b64 v[116:117], v50 offset:256
	ds_read_b64 v[118:119], v50 offset:288
	ds_read_b64 v[120:121], v52 offset:768
	ds_read_b64 v[122:123], v52 offset:800
	ds_read_b64 v[124:125], v53 offset:1280
	ds_read_b64 v[126:127], v53 offset:1312
	ds_read_b64 v[128:129], v51 offset:1792
	ds_read_b64 v[130:131], v51 offset:1824
	s_waitcnt lgkmcnt(12)
	v_add_f32_e32 v10, v10, v21
	v_sub_f32_e32 v21, v74, v86
	v_mul_f32_e32 v21, 0x3fb8aa3b, v21
	v_exp_f32_e32 v21, v21
	s_waitcnt lgkmcnt(10)
	v_mfma_f32_16x16x32_bf16 v[62:65], v[108:111], v[78:81], v[66:69]
	v_add_f32_e32 v10, v21, v10
	s_nop 1
	ds_read_b64 v[132:133], v50 offset:320
	ds_read_b64 v[134:135], v50 offset:352
	v_cvt_pk_bf16_f32 v20, v19, v20
	v_cvt_pk_bf16_f32 v21, v22, v26
	v_cvt_pk_bf16_f32 v22, v28, v31
	v_cvt_pk_bf16_f32 v23, v34, v29
	ds_read_b64 v[136:137], v52 offset:832
	ds_read_b64 v[138:139], v52 offset:864
	s_waitcnt lgkmcnt(10)
	v_mfma_f32_16x16x32_bf16 v[24:27], v[116:119], v[20:23], v[36:39]
	ds_read_b64 v[140:141], v53 offset:1344
	ds_read_b64 v[142:143], v53 offset:1376
	ds_read_b64 v[144:145], v51 offset:1856
	ds_read_b64 v[146:147], v51 offset:1888
	s_nop 0
	ds_read_b128 v[148:151], v44
	v_cvt_pk_bf16_f32 v12, v11, v12
	v_cvt_pk_bf16_f32 v13, v13, v14
	v_cvt_pk_bf16_f32 v14, v15, v16
	v_cvt_pk_bf16_f32 v15, v17, v18
	ds_read_b128 v[152:155], v44 offset:64
	s_waitcnt lgkmcnt(8)
	v_mfma_f32_16x16x32_bf16 v[16:19], v[132:135], v[12:15], v[24:27]
	s_nop 2
	ds_read_b128 v[168:171], v44 offset:18496
	v_div_scale_f32 v11, s[6:7], v10, v10, 1.0
	v_mfma_f32_16x16x32_bf16 v[28:31], v[120:123], v[20:23], v[46:49]
	s_waitcnt lgkmcnt(7)
	v_mfma_f32_16x16x32_bf16 v[24:27], v[136:139], v[12:15], v[28:31]
	s_nop 5
	ds_read_b128 v[172:175], v44 offset:2368
	v_mfma_f32_16x16x32_bf16 v[32:35], v[124:127], v[20:23], v[62:65]
	s_waitcnt lgkmcnt(6)
	v_mfma_f32_16x16x32_bf16 v[28:31], v[140:143], v[12:15], v[32:35]
	s_nop 5
	ds_read_b128 v[176:179], v44 offset:2304
	v_mfma_f32_16x16x32_bf16 v[58:61], v[112:115], v[78:81], v[58:61]
	v_mfma_f32_16x16x32_bf16 v[20:23], v[128:131], v[20:23], v[58:61]
	s_waitcnt lgkmcnt(5)
	v_mfma_f32_16x16x32_bf16 v[12:15], v[144:147], v[12:15], v[20:23]
	v_or_b32_e32 v34, 48, v75
	s_nop 4
	v_rcp_f32_e32 v20, v11
	s_nop 0
	v_fma_f32 v21, -v11, v20, 1.0
	v_fmac_f32_e32 v20, v21, v20
	v_div_scale_f32 v21, vcc, 1.0, v10, 1.0
	v_mul_f32_e32 v22, v21, v20
	v_fma_f32 v23, -v11, v22, v21
	v_fmac_f32_e32 v22, v23, v20
	v_fma_f32 v11, -v11, v22, v21
	v_div_fmas_f32 v11, v11, v20, v22
	v_div_fixup_f32 v20, v11, v10, 1.0
	v_lshlrev_b64 v[10:11], 11, v[42:43]
	v_lshl_add_u64 v[10:11], s[64:65], 0, v[10:11]
	v_mul_f32_e32 v16, v16, v20
	v_mul_f32_e32 v17, v17, v20
	v_lshl_add_u64 v[10:11], v[10:11], 0, s[10:11]
	v_cvt_pk_bf16_f32 v16, v16, v17
	v_mul_f32_e32 v17, v18, v20
	v_lshl_add_u64 v[10:11], v[10:11], 0, v[0:1]
	v_mul_f32_e32 v18, v19, v20
	v_cvt_pk_bf16_f32 v17, v17, v18
	global_store_dwordx2 v[10:11], v[16:17], off offset:512
	v_mul_f32_e32 v16, v24, v20
	v_mul_f32_e32 v17, v25, v20
	v_cvt_pk_bf16_f32 v16, v16, v17
	v_mul_f32_e32 v17, v26, v20
	v_mul_f32_e32 v18, v27, v20
	v_cvt_pk_bf16_f32 v17, v17, v18
	global_store_dwordx2 v[10:11], v[16:17], off offset:544
	v_mul_f32_e32 v16, v28, v20
	v_mul_f32_e32 v17, v29, v20
	v_cvt_pk_bf16_f32 v16, v16, v17
	v_mul_f32_e32 v17, v30, v20
	v_mul_f32_e32 v12, v20, v12
	v_mul_f32_e32 v13, v20, v13
	v_mul_f32_e32 v18, v31, v20
	v_cvt_pk_bf16_f32 v17, v17, v18
	global_store_dwordx2 v[10:11], v[16:17], off offset:576
	v_cvt_pk_bf16_f32 v12, v12, v13
	v_mul_f32_e32 v13, v20, v14
	v_mul_f32_e32 v14, v20, v15
	v_cvt_pk_bf16_f32 v13, v13, v14
	global_store_dwordx2 v[10:11], v[12:13], off offset:608
	ds_read_b128 v[180:183], v44 offset:4672
	ds_read_b128 v[184:187], v44 offset:4608
	s_waitcnt lgkmcnt(6)
	v_mfma_f32_16x16x32_bf16 v[10:13], v[148:151], v[6:9], 0
	ds_read_b128 v[188:191], v44 offset:6976
	s_waitcnt lgkmcnt(6)
	v_mfma_f32_16x16x32_bf16 v[38:41], v[152:155], v[2:5], v[10:13]
	ds_read_b128 v[108:111], v44 offset:6912
	s_nop 3
	ds_read_b128 v[112:115], v44 offset:9280
	s_waitcnt lgkmcnt(5)
; #define LAS __attribute__((address_space(3)))
; #define MFMA16(a, b, c) __builtin_amdgcn_mfma_f32_16x16x32_bf16((a), (b), (c), 0, 0, 0)
; __device__ __forceinline__ void attn_item(int item, const float* const* in, int l, unsigned char* ws, bf16_t* ybuf, LAS unsigned char* lds, int tid, int lane, int wave) {
;     ...
;         for (int r = 0; r < 10; ++r) { const LAS bf16_t* kp = KL + (16 * (2 * s_lo + r) + fr) * 72 + 8 * q;
;             f32x4 a = (f32x4){0.f, 0.f, 0.f, 0.f}; a = MFMA16(*(const LAS bf16x8*)kp, Bq0, a); a = MFMA16(*(const LAS bf16x8*)(kp + 32), Bq1, a); acc[r] = a; }
;         const int a1 = iq + 1, sft = (4 - (a1 & 3)) & 3, a4 = (a1 + sft) >> 2;
;         const LAS float* ct = CT + (hl * 4 + sft) * 384 + 128 + 4 * (4 * (2 * s_lo) + q - a4);
;         float mx = sink;
; #pragma unroll
;         for (int r = 0; r < 10; ++r) { const f32x4 tb = *(const LAS f32x4*)(ct + 16 * r); const bool dead = (nb == 0) && (2 * s_lo + r < 8);
; #pragma unroll
;             for (int jj = 0; jj < 4; ++jj) { float sc = acc[r][jj] * 0.125f + tb[jj]; sc = dead ? NEG_INF : sc; acc[r][jj] = sc; mx = fmaxf(mx, sc); } }
	v_mfma_f32_16x16x32_bf16 v[10:13], v[176:179], v[6:9], 0
	v_mfma_f32_16x16x32_bf16 v[46:49], v[172:175], v[2:5], v[10:13]
	ds_read_b128 v[116:119], v44 offset:9216
	s_nop 5
	ds_read_b128 v[120:123], v44 offset:11584
	s_waitcnt lgkmcnt(5)
	v_mfma_f32_16x16x32_bf16 v[10:13], v[184:187], v[6:9], 0
	v_mfma_f32_16x16x32_bf16 v[58:61], v[180:183], v[2:5], v[10:13]
	ds_read_b128 v[124:127], v44 offset:11520
	s_nop 5
	ds_read_b128 v[128:131], v44 offset:13888
	s_waitcnt lgkmcnt(5)
	v_mfma_f32_16x16x32_bf16 v[10:13], v[108:111], v[6:9], 0
	v_mfma_f32_16x16x32_bf16 v[30:33], v[188:191], v[2:5], v[10:13]
	ds_read_b128 v[132:135], v44 offset:13824
	s_nop 5
	ds_read_b128 v[136:139], v44 offset:16192
	s_waitcnt lgkmcnt(5)
	v_mfma_f32_16x16x32_bf16 v[10:13], v[116:119], v[6:9], 0
	v_mfma_f32_16x16x32_bf16 v[26:29], v[112:115], v[2:5], v[10:13]
	ds_read_b128 v[140:143], v44 offset:16128
	s_nop 5
	ds_read_b128 v[144:147], v44 offset:18432
	s_waitcnt lgkmcnt(5)
	v_mfma_f32_16x16x32_bf16 v[10:13], v[124:127], v[6:9], 0
	v_mfma_f32_16x16x32_bf16 v[22:25], v[120:123], v[2:5], v[10:13]
	ds_read_b128 v[148:151], v44 offset:20736
	s_nop 5
	ds_read_b128 v[152:155], v44 offset:20800
	s_waitcnt lgkmcnt(5)
	v_mfma_f32_16x16x32_bf16 v[10:13], v[132:135], v[6:9], 0
	v_mfma_f32_16x16x32_bf16 v[18:21], v[128:131], v[2:5], v[10:13]
	s_nop 0
	s_nop 5
	s_nop 0
	s_waitcnt lgkmcnt(3)
	v_mfma_f32_16x16x32_bf16 v[10:13], v[140:143], v[6:9], 0
	v_mfma_f32_16x16x32_bf16 v[14:17], v[136:139], v[2:5], v[10:13]
	s_nop 6
	s_nop 0
	s_waitcnt lgkmcnt(2)
	v_mfma_f32_16x16x32_bf16 v[10:13], v[144:147], v[6:9], 0
	v_mfma_f32_16x16x32_bf16 v[10:13], v[168:171], v[2:5], v[10:13]
	s_nop 0
	s_waitcnt lgkmcnt(1)
	v_mfma_f32_16x16x32_bf16 v[6:9], v[148:151], v[6:9], 0
	s_nop 0
	s_waitcnt lgkmcnt(0)
	v_mfma_f32_16x16x32_bf16 v[2:5], v[152:155], v[2:5], v[6:9]
	s_nop 4
	v_sub_u32_e32 v6, v34, v76
	v_lshrrev_b32_e32 v6, 2, v6
	v_sub_u32_e32 v6, v45, v6
	v_lshl_add_u32 v42, v6, 4, v77
	ds_read_b128 v[6:9], v42 offset:512
	s_waitcnt lgkmcnt(0)
	v_fmamk_f32 v6, v38, 0x3e000000, v6
	v_cndmask_b32_e64 v38, v6, v236, s[42:43]
	v_fmamk_f32 v6, v39, 0x3e000000, v7
	v_cndmask_b32_e64 v37, v6, v236, s[42:43]
	v_fmamk_f32 v7, v40, 0x3e000000, v8
	v_fmac_f32_e32 v9, 0x3e000000, v41
	v_max3_f32 v6, v74, v38, v37
	v_cndmask_b32_e64 v36, v7, v236, s[42:43]
	v_cndmask_b32_e64 v35, v9, v236, s[42:43]
	v_max3_f32 v39, v6, v36, v35
	ds_read_b128 v[6:9], v42 offset:576
	s_waitcnt lgkmcnt(0)
	v_fmamk_f32 v6, v46, 0x3e000000, v6
	v_cndmask_b32_e64 v40, v6, v236, s[42:43]
	v_fmamk_f32 v6, v47, 0x3e000000, v7
	v_cndmask_b32_e64 v41, v6, v236, s[42:43]
	v_fmamk_f32 v7, v48, 0x3e000000, v8
	v_fmac_f32_e32 v9, 0x3e000000, v49
	v_max3_f32 v6, v39, v40, v41
	v_cndmask_b32_e64 v39, v7, v236, s[42:43]
	v_cndmask_b32_e64 v44, v9, v236, s[42:43]
	v_max3_f32 v45, v6, v39, v44
	ds_read_b128 v[108:111], v42 offset:640
	ds_read_b128 v[112:115], v42 offset:704
	ds_read_b128 v[116:119], v42 offset:768
	ds_read_b128 v[120:123], v42 offset:832
	ds_read_b128 v[124:127], v42 offset:896
	ds_read_b128 v[128:131], v42 offset:960
	s_waitcnt lgkmcnt(5)
	v_fmamk_f32 v6, v58, 0x3e000000, v108
	v_cndmask_b32_e64 v46, v6, v236, s[44:45]
	v_fmamk_f32 v6, v59, 0x3e000000, v109
	v_cndmask_b32_e64 v47, v6, v236, s[44:45]
	v_fmamk_f32 v7, v60, 0x3e000000, v110
	v_mov_b32_e32 v9, v111
	v_fmac_f32_e32 v9, 0x3e000000, v61
	v_max3_f32 v6, v45, v46, v47
	v_cndmask_b32_e64 v45, v7, v236, s[44:45]
	v_cndmask_b32_e64 v48, v9, v236, s[44:45]
	v_max3_f32 v49, v6, v45, v48
	ds_read_b128 v[132:135], v42 offset:1024
	s_waitcnt lgkmcnt(5)
	v_fmamk_f32 v6, v30, 0x3e000000, v112
	v_cndmask_b32_e64 v30, v6, v236, s[44:45]
	v_fmamk_f32 v6, v31, 0x3e000000, v113
	v_cndmask_b32_e64 v58, v6, v236, s[44:45]
	v_fmamk_f32 v7, v32, 0x3e000000, v114
	v_mov_b32_e32 v9, v115
	v_fmac_f32_e32 v9, 0x3e000000, v33
	v_max3_f32 v6, v49, v30, v58
	v_cndmask_b32_e64 v49, v7, v236, s[44:45]
	v_cndmask_b32_e64 v33, v9, v236, s[44:45]
	v_max3_f32 v31, v6, v49, v33
	ds_read_b128 v[136:139], v42 offset:1088
	s_waitcnt lgkmcnt(5)
	v_fmamk_f32 v6, v26, 0x3e000000, v116
	v_cndmask_b32_e64 v26, v6, v236, s[44:45]
	v_fmamk_f32 v6, v27, 0x3e000000, v117
	v_cndmask_b32_e64 v59, v6, v236, s[44:45]
	v_fmamk_f32 v7, v28, 0x3e000000, v118
	v_mov_b32_e32 v9, v119
	v_fmac_f32_e32 v9, 0x3e000000, v29
	v_max3_f32 v6, v31, v26, v59
	v_cndmask_b32_e64 v28, v7, v236, s[44:45]
	v_cndmask_b32_e64 v60, v9, v236, s[44:45]
	v_max3_f32 v27, v6, v28, v60
	s_nop 0
	s_waitcnt lgkmcnt(4)
	v_fmamk_f32 v6, v22, 0x3e000000, v120
	v_cndmask_b32_e64 v61, v6, v236, s[44:45]
	v_fmamk_f32 v6, v23, 0x3e000000, v121
	v_cndmask_b32_e64 v23, v6, v236, s[44:45]
	v_fmamk_f32 v7, v24, 0x3e000000, v122
	v_mov_b32_e32 v9, v123
	v_fmac_f32_e32 v9, 0x3e000000, v25
	v_max3_f32 v6, v27, v61, v23
	v_cndmask_b32_e64 v62, v7, v236, s[44:45]
	v_cndmask_b32_e64 v63, v9, v236, s[44:45]
	v_max3_f32 v22, v6, v62, v63
	s_nop 0
	s_waitcnt lgkmcnt(3)
	v_fmamk_f32 v6, v18, 0x3e000000, v124
	v_fmamk_f32 v7, v19, 0x3e000000, v125
	v_max3_f32 v18, v22, v6, v7
	v_fmamk_f32 v8, v20, 0x3e000000, v126
	v_mov_b32_e32 v9, v127
	v_fmac_f32_e32 v9, 0x3e000000, v21
	v_max3_f32 v22, v18, v8, v9
	s_nop 0
	s_waitcnt lgkmcnt(2)
	v_fmamk_f32 v64, v14, 0x3e000000, v128
	v_fmamk_f32 v65, v15, 0x3e000000, v129
	v_max3_f32 v14, v22, v64, v65
	v_fmamk_f32 v66, v16, 0x3e000000, v130
	v_mov_b32_e32 v21, v131
	v_fmac_f32_e32 v21, 0x3e000000, v17
	v_max3_f32 v18, v14, v66, v21
	s_nop 0
	s_waitcnt lgkmcnt(1)
	v_fmamk_f32 v67, v10, 0x3e000000, v132
	v_fmamk_f32 v68, v11, 0x3e000000, v133
	v_max3_f32 v10, v18, v67, v68
	v_fmamk_f32 v69, v12, 0x3e000000, v134
	v_mov_b32_e32 v17, v135
	v_fmac_f32_e32 v17, 0x3e000000, v13
	v_max3_f32 v14, v10, v69, v17
	s_nop 0
	s_waitcnt lgkmcnt(0)
; #define LAS __attribute__((address_space(3)))
; __device__ __forceinline__ unsigned pk2(float lo, float hi) { return pg8::cvt_pk_bf16(lo, hi); }
; #define MFMA16(a, b, c) __builtin_amdgcn_mfma_f32_16x16x32_bf16((a), (b), (c), 0, 0, 0)
; __device__ __forceinline__ void attn_item(int item, const float* const* in, int l, unsigned char* ws, bf16_t* ybuf, LAS unsigned char* lds, int tid, int lane, int wave) {
;     ...
;         float mx = sink;
; #pragma unroll
;         for (int r = 0; r < 10; ++r) { const f32x4 tb = *(const LAS f32x4*)(ct + 16 * r); const bool dead = (nb == 0) && (2 * s_lo + r < 8);
; #pragma unroll
;             for (int jj = 0; jj < 4; ++jj) { float sc = acc[r][jj] * 0.125f + tb[jj]; sc = dead ? NEG_INF : sc; acc[r][jj] = sc; mx = fmaxf(mx, sc); } }
;         mx = fmaxf(mx, __shfl_xor(mx, 16)); mx = fmaxf(mx, __shfl_xor(mx, 32));
;         float sum = 0.f;
; #pragma unroll
;         for (int r = 0; r < 10; ++r)
; #pragma unroll
;             for (int jj = 0; jj < 4; ++jj) { const float ev = __expf(acc[r][jj] - mx); acc[r][jj] = ev; sum += ev; }
;         sum += __shfl_xor(sum, 16); sum += __shfl_xor(sum, 32);
;         const float inv = 1.0f / (sum + __expf(sink - mx));
;         f32x4 o[4];
; #pragma unroll
;         for (int df = 0; df < 4; ++df) o[df] = (f32x4){0.f, 0.f, 0.f, 0.f};
; #pragma unroll
;         for (int s = 0; s < 5; ++s) {
;             u32x4v pw; pw.x = pk2(acc[2 * s][0], acc[2 * s][1]); pw.y = pk2(acc[2 * s][2], acc[2 * s][3]); pw.z = pk2(acc[2 * s + 1][0], acc[2 * s + 1][1]); pw.w = pk2(acc[2 * s + 1][2], acc[2 * s + 1][3]);
;             const bf16x8 P = __builtin_bit_cast(bf16x8, pw);
; #pragma unroll
;             for (int df = 0; df < 4; ++df) { const LAS bf16_t* vp = VT + (16 * df + fr) * 272 + 32 * (s_lo + s) + 4 * q;
;                 const u32x2v lo = *(const LAS u32x2v*)vp, hi = *(const LAS u32x2v*)(vp + 16);
;                 u32x4v aw; aw.x = lo.x; aw.y = lo.y; aw.z = hi.x; aw.w = hi.y;
;                 o[df] = MFMA16(__builtin_bit_cast(bf16x8, aw), P, o[df]); }
	v_fmamk_f32 v2, v2, 0x3e000000, v136
	v_fmamk_f32 v10, v3, 0x3e000000, v137
	v_max3_f32 v3, v14, v2, v10
	s_waitcnt lgkmcnt(0)
	v_mov_b32_e32 v12, v138
	v_mov_b32_e32 v13, v139
	s_nop 1
	v_fmamk_f32 v42, v4, 0x3e000000, v12
	v_fmac_f32_e32 v13, 0x3e000000, v5
	v_max3_f32 v3, v3, v42, v13
	ds_bpermute_b32 v4, v72, v3
	s_waitcnt lgkmcnt(0)
	v_max_f32_e32 v4, v4, v4
	v_max_f32_e32 v3, v3, v4
	ds_bpermute_b32 v4, v73, v3
	s_waitcnt lgkmcnt(0)
	v_max_f32_e32 v4, v4, v4
	v_max_f32_e32 v70, v3, v4
	v_sub_f32_e32 v4, v37, v70
	v_mul_f32_e32 v4, 0x3fb8aa3b, v4
	v_exp_f32_e32 v31, v4
	v_sub_f32_e32 v4, v36, v70
	v_mul_f32_e32 v4, 0x3fb8aa3b, v4
	v_exp_f32_e32 v36, v4
	v_sub_f32_e32 v4, v35, v70
	v_mul_f32_e32 v4, 0x3fb8aa3b, v4
	v_exp_f32_e32 v37, v4
	v_sub_f32_e32 v4, v40, v70
	v_mul_f32_e32 v4, 0x3fb8aa3b, v4
	v_exp_f32_e32 v40, v4
	v_sub_f32_e32 v4, v41, v70
	v_mul_f32_e32 v4, 0x3fb8aa3b, v4
	v_exp_f32_e32 v41, v4
	v_sub_f32_e32 v4, v39, v70
	v_mul_f32_e32 v4, 0x3fb8aa3b, v4
	v_exp_f32_e32 v71, v4
	v_sub_f32_e32 v4, v44, v70
	v_mul_f32_e32 v4, 0x3fb8aa3b, v4
	v_exp_f32_e32 v44, v4
	v_sub_f32_e32 v4, v46, v70
	v_mul_f32_e32 v4, 0x3fb8aa3b, v4
	v_exp_f32_e32 v22, v4
	v_sub_f32_e32 v4, v47, v70
	v_mul_f32_e32 v4, 0x3fb8aa3b, v4
	v_exp_f32_e32 v24, v4
	v_sub_f32_e32 v4, v45, v70
	v_mul_f32_e32 v4, 0x3fb8aa3b, v4
	v_exp_f32_e32 v27, v4
	v_sub_f32_e32 v4, v48, v70
	v_mul_f32_e32 v4, 0x3fb8aa3b, v4
	v_exp_f32_e32 v32, v4
	v_sub_f32_e32 v4, v30, v70
	v_mul_f32_e32 v4, 0x3fb8aa3b, v4
	v_exp_f32_e32 v35, v4
	v_sub_f32_e32 v4, v58, v70
	v_mul_f32_e32 v4, 0x3fb8aa3b, v4
	v_exp_f32_e32 v48, v4
	v_sub_f32_e32 v4, v49, v70
	v_mul_f32_e32 v4, 0x3fb8aa3b, v4
	v_exp_f32_e32 v49, v4
	v_sub_f32_e32 v4, v33, v70
	v_sub_f32_e32 v3, v38, v70
	v_mul_f32_e32 v4, 0x3fb8aa3b, v4
	v_mul_f32_e32 v3, 0x3fb8aa3b, v3
	v_exp_f32_e32 v75, v4
	v_sub_f32_e32 v4, v26, v70
	v_exp_f32_e32 v29, v3
	v_mul_f32_e32 v4, 0x3fb8aa3b, v4
	v_exp_f32_e32 v15, v4
	v_sub_f32_e32 v4, v59, v70
	v_mul_f32_e32 v4, 0x3fb8aa3b, v4
	v_exp_f32_e32 v16, v4
	v_sub_f32_e32 v4, v28, v70
	v_add_f32_e32 v3, 0, v29
	v_mul_f32_e32 v4, 0x3fb8aa3b, v4
	v_add_f32_e32 v3, v31, v3
	v_exp_f32_e32 v19, v4
	v_sub_f32_e32 v4, v60, v70
	v_add_f32_e32 v3, v36, v3
	v_mul_f32_e32 v4, 0x3fb8aa3b, v4
	v_add_f32_e32 v3, v37, v3
	v_exp_f32_e32 v25, v4
	v_sub_f32_e32 v4, v61, v70
	v_add_f32_e32 v3, v40, v3
	v_mul_f32_e32 v4, 0x3fb8aa3b, v4
	v_add_f32_e32 v3, v41, v3
	v_exp_f32_e32 v28, v4
	v_sub_f32_e32 v4, v23, v70
	v_add_f32_e32 v3, v71, v3
	v_mul_f32_e32 v4, 0x3fb8aa3b, v4
	v_add_f32_e32 v3, v44, v3
	v_exp_f32_e32 v30, v4
	v_sub_f32_e32 v4, v62, v70
	v_add_f32_e32 v3, v22, v3
	v_mul_f32_e32 v4, 0x3fb8aa3b, v4
	v_add_f32_e32 v3, v24, v3
	v_exp_f32_e32 v33, v4
	v_sub_f32_e32 v4, v63, v70
	v_add_f32_e32 v3, v27, v3
	v_mul_f32_e32 v4, 0x3fb8aa3b, v4
	v_add_f32_e32 v3, v32, v3
	v_exp_f32_e32 v76, v4
	v_sub_f32_e32 v4, v6, v70
	v_add_f32_e32 v3, v35, v3
	v_mul_f32_e32 v4, 0x3fb8aa3b, v4
	v_add_f32_e32 v3, v48, v3
	v_exp_f32_e32 v11, v4
	v_sub_f32_e32 v4, v7, v70
	v_add_f32_e32 v3, v49, v3
	v_mul_f32_e32 v4, 0x3fb8aa3b, v4
	v_add_f32_e32 v3, v75, v3
	v_exp_f32_e32 v12, v4
	v_sub_f32_e32 v4, v8, v70
	v_add_f32_e32 v3, v15, v3
	v_mul_f32_e32 v4, 0x3fb8aa3b, v4
	v_add_f32_e32 v3, v16, v3
	v_exp_f32_e32 v14, v4
	v_sub_f32_e32 v4, v9, v70
	v_add_f32_e32 v3, v19, v3
	v_mul_f32_e32 v4, 0x3fb8aa3b, v4
	v_add_f32_e32 v3, v25, v3
	v_exp_f32_e32 v18, v4
	v_sub_f32_e32 v4, v64, v70
	v_add_f32_e32 v3, v28, v3
	v_mul_f32_e32 v4, 0x3fb8aa3b, v4
	v_add_f32_e32 v3, v30, v3
	v_exp_f32_e32 v20, v4
	v_sub_f32_e32 v4, v65, v70
	v_add_f32_e32 v3, v33, v3
	v_mul_f32_e32 v4, 0x3fb8aa3b, v4
	v_add_f32_e32 v3, v76, v3
	v_exp_f32_e32 v23, v4
	v_sub_f32_e32 v4, v66, v70
	v_add_f32_e32 v3, v11, v3
	v_mul_f32_e32 v4, 0x3fb8aa3b, v4
	v_add_f32_e32 v3, v12, v3
	v_exp_f32_e32 v26, v4
	v_sub_f32_e32 v4, v21, v70
	v_add_f32_e32 v3, v14, v3
	v_mul_f32_e32 v4, 0x3fb8aa3b, v4
	v_add_f32_e32 v3, v18, v3
	v_exp_f32_e32 v21, v4
	v_add_f32_e32 v3, v20, v3
	v_add_f32_e32 v3, v23, v3
	v_add_f32_e32 v3, v26, v3
	v_add_f32_e32 v4, v21, v3
	v_sub_f32_e32 v3, v67, v70
	v_mul_f32_e32 v3, 0x3fb8aa3b, v3
	v_exp_f32_e32 v3, v3
	v_cvt_pk_bf16_f32 v38, v29, v31
	v_cvt_pk_bf16_f32 v39, v36, v37
	v_cvt_pk_bf16_f32 v40, v40, v41
	v_cvt_pk_bf16_f32 v41, v71, v44
	ds_read_b64 v[108:109], v57
	ds_read_b64 v[110:111], v57 offset:32
	ds_read_b64 v[112:113], v55 offset:512
	ds_read_b64 v[114:115], v55 offset:544
	ds_read_b64 v[116:117], v56 offset:1024
	ds_read_b64 v[118:119], v56 offset:1056
	ds_read_b64 v[120:121], v54 offset:1536
	ds_read_b64 v[122:123], v54 offset:1568
	s_nop 0
	s_nop 0
	s_nop 0
	v_add_f32_e32 v5, v3, v4
	v_sub_f32_e32 v4, v68, v70
	v_mul_f32_e32 v4, 0x3fb8aa3b, v4
	v_exp_f32_e32 v4, v4
	s_waitcnt lgkmcnt(6)
	v_mfma_f32_16x16x32_bf16 v[44:47], v[108:111], v[38:41], 0
	v_sub_f32_e32 v2, v2, v70
	v_add_f32_e32 v6, v4, v5
	v_sub_f32_e32 v5, v69, v70
	s_waitcnt lgkmcnt(4)
	v_mfma_f32_16x16x32_bf16 v[58:61], v[112:115], v[38:41], 0
	v_mul_f32_e32 v5, 0x3fb8aa3b, v5
	v_exp_f32_e32 v5, v5
	v_mul_f32_e32 v2, 0x3fb8aa3b, v2
	s_waitcnt lgkmcnt(2)
	v_mfma_f32_16x16x32_bf16 v[62:65], v[116:119], v[38:41], 0
	v_sub_f32_e32 v9, v42, v70
	v_add_f32_e32 v7, v5, v6
	v_sub_f32_e32 v6, v17, v70
	s_waitcnt lgkmcnt(0)
; #define LAS __attribute__((address_space(3)))
; __device__ __forceinline__ unsigned pk2(float lo, float hi) { return pg8::cvt_pk_bf16(lo, hi); }
; #define MFMA16(a, b, c) __builtin_amdgcn_mfma_f32_16x16x32_bf16((a), (b), (c), 0, 0, 0)
; __device__ __forceinline__ void attn_item(int item, const float* const* in, int l, unsigned char* ws, bf16_t* ybuf, LAS unsigned char* lds, int tid, int lane, int wave) {
;     ...
;         float sum = 0.f;
; #pragma unroll
;         for (int r = 0; r < 10; ++r)
; #pragma unroll
;             for (int jj = 0; jj < 4; ++jj) { const float ev = __expf(acc[r][jj] - mx); acc[r][jj] = ev; sum += ev; }
;         sum += __shfl_xor(sum, 16); sum += __shfl_xor(sum, 32);
;         const float inv = 1.0f / (sum + __expf(sink - mx));
;         f32x4 o[4];
; #pragma unroll
;         for (int df = 0; df < 4; ++df) o[df] = (f32x4){0.f, 0.f, 0.f, 0.f};
; #pragma unroll
;         for (int s = 0; s < 5; ++s) {
;             u32x4v pw; pw.x = pk2(acc[2 * s][0], acc[2 * s][1]); pw.y = pk2(acc[2 * s][2], acc[2 * s][3]); pw.z = pk2(acc[2 * s + 1][0], acc[2 * s + 1][1]); pw.w = pk2(acc[2 * s + 1][2], acc[2 * s + 1][3]);
;             const bf16x8 P = __builtin_bit_cast(bf16x8, pw);
; #pragma unroll
;             for (int df = 0; df < 4; ++df) { const LAS bf16_t* vp = VT + (16 * df + fr) * 272 + 32 * (s_lo + s) + 4 * q;
;                 const u32x2v lo = *(const LAS u32x2v*)vp, hi = *(const LAS u32x2v*)(vp + 16);
;                 u32x4v aw; aw.x = lo.x; aw.y = lo.y; aw.z = hi.x; aw.w = hi.y;
;                 o[df] = MFMA16(__builtin_bit_cast(bf16x8, aw), P, o[df]); }
;         }
; #pragma unroll
;         for (int df = 0; df < 4; ++df) { u32x2v w; w.x = pk2(o[df][0] * inv, o[df][1] * inv); w.y = pk2(o[df][2] * inv, o[df][3] * inv);
;             *(u32x2v*)(Y + gt * D + 256 + hq * 64 + 16 * df + 4 * q) = w; }
	v_mfma_f32_16x16x32_bf16 v[36:39], v[120:123], v[38:41], 0
	v_cvt_pk_bf16_f32 v54, v22, v24
	v_cvt_pk_bf16_f32 v55, v27, v32
	v_cvt_pk_bf16_f32 v56, v35, v48
	v_cvt_pk_bf16_f32 v57, v49, v75
	ds_read_b64 v[108:109], v50 offset:128
	ds_read_b64 v[110:111], v50 offset:160
	ds_read_b64 v[112:113], v52 offset:640
	ds_read_b64 v[114:115], v52 offset:672
	ds_read_b64 v[116:117], v53 offset:1152
	ds_read_b64 v[118:119], v53 offset:1184
	ds_read_b64 v[120:121], v51 offset:1664
	ds_read_b64 v[122:123], v51 offset:1696
	ds_read_b64 v[124:125], v50 offset:192
	ds_read_b64 v[126:127], v50 offset:224
	s_waitcnt lgkmcnt(8)
	v_mfma_f32_16x16x32_bf16 v[44:47], v[108:111], v[54:57], v[44:47]
	s_nop 0
	v_mul_f32_e32 v6, 0x3fb8aa3b, v6
	v_exp_f32_e32 v6, v6
	s_waitcnt lgkmcnt(6)
	v_mfma_f32_16x16x32_bf16 v[58:61], v[112:115], v[54:57], v[58:61]
	s_nop 0
	v_add_f32_e32 v8, v6, v7
	v_exp_f32_e32 v7, v2
	s_waitcnt lgkmcnt(4)
	v_mfma_f32_16x16x32_bf16 v[62:65], v[116:119], v[54:57], v[62:65]
	s_nop 0
	v_add_f32_e32 v2, v7, v8
	v_sub_f32_e32 v8, v10, v70
	v_mul_f32_e32 v8, 0x3fb8aa3b, v8
	v_exp_f32_e32 v8, v8
	v_mul_f32_e32 v9, 0x3fb8aa3b, v9
	v_sub_f32_e32 v10, v13, v70
	v_exp_f32_e32 v9, v9
	v_mul_f32_e32 v10, 0x3fb8aa3b, v10
	v_exp_f32_e32 v10, v10
	v_add_f32_e32 v2, v8, v2
	v_add_f32_e32 v2, v9, v2
	v_or_b32_e32 v42, s0, v34
	v_add_f32_e32 v2, v10, v2
	s_waitcnt lgkmcnt(2)
	v_mfma_f32_16x16x32_bf16 v[34:37], v[120:123], v[54:57], v[36:39]
	v_cvt_pk_bf16_f32 v38, v15, v16
	v_cvt_pk_bf16_f32 v39, v19, v25
	v_cvt_pk_bf16_f32 v40, v28, v30
	v_cvt_pk_bf16_f32 v41, v33, v76
	s_nop 0
	s_waitcnt lgkmcnt(0)
	v_mov_b32_e32 v28, v124
	v_mov_b32_e32 v29, v125
	v_mov_b32_e32 v30, v126
	v_mov_b32_e32 v31, v127
	s_nop 1
	ds_bpermute_b32 v13, v72, v2
	s_waitcnt lgkmcnt(1)
	v_mfma_f32_16x16x32_bf16 v[28:31], v[28:31], v[38:41], v[44:47]
	s_waitcnt lgkmcnt(0)
	v_add_f32_e32 v2, v2, v13
	ds_bpermute_b32 v13, v73, v2
	ds_read_b64 v[108:109], v52 offset:704
	ds_read_b64 v[110:111], v52 offset:736
	ds_read_b64 v[112:113], v53 offset:1216
	ds_read_b64 v[114:115], v53 offset:1248
	ds_read_b64 v[116:117], v51 offset:1728
	ds_read_b64 v[118:119], v51 offset:1760
	ds_read_b64 v[120:121], v50 offset:256
	ds_read_b64 v[122:123], v50 offset:288
	ds_read_b64 v[124:125], v52 offset:768
	ds_read_b64 v[126:127], v52 offset:800
	ds_read_b64 v[128:129], v53 offset:1280
	ds_read_b64 v[130:131], v53 offset:1312
	s_waitcnt lgkmcnt(10)
	v_mfma_f32_16x16x32_bf16 v[44:47], v[108:111], v[38:41], v[58:61]
	v_add_f32_e32 v2, v2, v13
	v_sub_f32_e32 v13, v74, v70
	v_mul_f32_e32 v13, 0x3fb8aa3b, v13
	v_exp_f32_e32 v13, v13
	ds_read_b64 v[132:133], v51 offset:1792
	ds_read_b64 v[134:135], v51 offset:1824
	ds_read_b64 v[136:137], v50 offset:320
	ds_read_b64 v[138:139], v50 offset:352
	v_cvt_pk_bf16_f32 v12, v11, v12
	v_add_f32_e32 v2, v13, v2
	v_cvt_pk_bf16_f32 v13, v14, v18
	v_cvt_pk_bf16_f32 v14, v20, v23
	v_cvt_pk_bf16_f32 v15, v26, v21
	ds_read_b64 v[140:141], v52 offset:832
	ds_read_b64 v[142:143], v52 offset:864
	s_waitcnt lgkmcnt(10)
	v_mfma_f32_16x16x32_bf16 v[16:19], v[120:123], v[12:15], v[28:31]
	ds_read_b64 v[144:145], v53 offset:1344
	ds_read_b64 v[146:147], v53 offset:1376
	ds_read_b64 v[108:109], v51 offset:1856
	ds_read_b64 v[110:111], v51 offset:1888
	s_nop 0
	s_nop 0
	v_cvt_pk_bf16_f32 v4, v3, v4
	v_cvt_pk_bf16_f32 v5, v5, v6
	v_cvt_pk_bf16_f32 v6, v7, v8
	v_cvt_pk_bf16_f32 v7, v9, v10
	s_nop 0
	s_waitcnt lgkmcnt(6)
	v_mfma_f32_16x16x32_bf16 v[8:11], v[136:139], v[4:7], v[16:19]
	s_nop 2
	s_nop 0
	v_div_scale_f32 v3, s[0:1], v2, v2, 1.0
	v_mfma_f32_16x16x32_bf16 v[20:23], v[124:127], v[12:15], v[44:47]
	s_waitcnt lgkmcnt(4)
	v_mfma_f32_16x16x32_bf16 v[16:19], v[140:143], v[4:7], v[20:23]
	s_nop 5
	s_nop 0
	v_mfma_f32_16x16x32_bf16 v[54:57], v[112:115], v[38:41], v[62:65]
	v_mfma_f32_16x16x32_bf16 v[24:27], v[128:131], v[12:15], v[54:57]
	s_waitcnt lgkmcnt(2)
	v_mfma_f32_16x16x32_bf16 v[20:23], v[144:147], v[4:7], v[24:27]
	v_mfma_f32_16x16x32_bf16 v[32:35], v[116:119], v[38:41], v[34:37]
	s_nop 4
	s_nop 0
	v_mfma_f32_16x16x32_bf16 v[12:15], v[132:135], v[12:15], v[32:35]
	s_waitcnt lgkmcnt(0)
	v_mfma_f32_16x16x32_bf16 v[4:7], v[108:111], v[4:7], v[12:15]
	s_nop 5
	v_rcp_f32_e32 v12, v3
	s_nop 0
	v_fma_f32 v13, -v3, v12, 1.0
	v_fmac_f32_e32 v12, v13, v12
	v_div_scale_f32 v13, vcc, 1.0, v2, 1.0
	v_mul_f32_e32 v14, v13, v12
	v_fma_f32 v15, -v3, v14, v13
	v_fmac_f32_e32 v14, v15, v12
	v_fma_f32 v3, -v3, v14, v13
	v_div_fmas_f32 v3, v3, v12, v14
	v_div_fixup_f32 v12, v3, v2, 1.0
	v_lshlrev_b64 v[2:3], 11, v[42:43]
	v_lshl_add_u64 v[2:3], s[64:65], 0, v[2:3]
	v_lshl_add_u64 v[2:3], v[2:3], 0, s[10:11]
	v_lshl_add_u64 v[2:3], v[2:3], 0, v[0:1]
	v_mul_f32_e32 v0, v8, v12
	v_mul_f32_e32 v8, v9, v12
	v_cvt_pk_bf16_f32 v8, v0, v8
	v_mul_f32_e32 v0, v10, v12
	v_mul_f32_e32 v9, v11, v12
	v_cvt_pk_bf16_f32 v9, v0, v9
	global_store_dwordx2 v[2:3], v[8:9], off offset:512
	v_mul_f32_e32 v0, v16, v12
	v_mul_f32_e32 v8, v17, v12
	v_cvt_pk_bf16_f32 v8, v0, v8
	v_mul_f32_e32 v0, v18, v12
	v_mul_f32_e32 v9, v19, v12
	v_cvt_pk_bf16_f32 v9, v0, v9
	global_store_dwordx2 v[2:3], v[8:9], off offset:544
	v_mul_f32_e32 v0, v20, v12
	v_mul_f32_e32 v8, v21, v12
	v_cvt_pk_bf16_f32 v8, v0, v8
	v_mul_f32_e32 v0, v22, v12
	v_mul_f32_e32 v9, v23, v12
	v_cvt_pk_bf16_f32 v9, v0, v9
	v_mul_f32_e32 v0, v12, v4
	v_mul_f32_e32 v4, v12, v5
	v_mul_f32_e32 v5, v12, v7
	global_store_dwordx2 v[2:3], v[8:9], off offset:576
	v_cvt_pk_bf16_f32 v4, v0, v4
	v_mul_f32_e32 v0, v12, v6
	v_cvt_pk_bf16_f32 v5, v0, v5
	global_store_dwordx2 v[2:3], v[4:5], off offset:608
	s_cbranch_scc1 .LBB0_813
